# phases 1/4/6 store outputs with sc1 (write-through), grid barriers after them skip the leader L2 write-back
# baseline (speedup 1.0000x reference)
; DI bf16_t f2bf(float a) { return (bf16_t)(pack2(a, 0.f) & 0xffffu); }
;   DI void operator()(const f32x4 (&acc)[2][2][4][2], const Unit& u, int wr, int wc, int fr, int fq) const {
;     const int row0 = u.pm * BM + wr * 64 + fr;
;     const int cl = wc * 32 + 8 * fq;
;     const int which = (u.pn == 3) ? 0 : (u.pn == 4) ? 1 : (u.pn == 8) ? 2 : -1;
; #pragma unroll
;     for (int ai = 0; ai < 2; ++ai)
; #pragma unroll
;       for (int m = 0; m < 4; ++m) {
;         const int row = row0 + ai * HALF + m * 16;
;         *(u32x4*)(H + (size_t)row * HS + u.pn * BM + cl) = pack8(acc[ai][0][m][0], acc[ai][0][m][1]);
;         if (which < 0) {
;           *(u32x4*)(H + (size_t)row * HS + u.pn * BM + HALF + cl) = pack8(acc[ai][1][m][0], acc[ai][1][m][1]);
;         } else {
;           const int b = row >> 11, t = row & 2047;
;           bf16_t* vp = VT + ((size_t)((which * 8 + b) * 128 + cl)) * 2048 + t;
; #pragma unroll
;           for (int j = 0; j < 4; ++j) { vp[(size_t)j * 2048] = f2bf(acc[ai][1][m][0][j]); vp[(size_t)(4 + j) * 2048] = f2bf(acc[ai][1][m][1][j]); }
;         }
;       }
;   }
.LBB0_240:
	v_lshl_add_u32 v146, s50, 8, v139
	v_ashrrev_i32_e32 v148, 4, v146
	v_cvt_pk_bf16_f32 v126, v126, v127
	v_cvt_pk_bf16_f32 v127, v128, v129
	v_cvt_pk_bf16_f32 v128, v122, v123
	v_mov_b64_e32 v[122:123], s[34:35]
	s_cmp_gt_i32 s39, -1
	v_lshl_or_b32 v147, s39, 10, v138
	v_and_b32_e32 v148, 0xffffff80, v148
	v_mad_i64_i32 v[122:123], s[4:5], v146, s87, v[122:123]
	s_cselect_b64 s[50:51], -1, 0
	v_add_u32_e32 v148, v147, v148
	s_lshl_b32 s4, s38, 8
	v_ashrrev_i32_e32 v149, 31, v148
	s_ashr_i32 s5, s4, 31
	v_lshlrev_b64 v[148:149], 12, v[148:149]
	v_lshl_add_u64 v[122:123], s[4:5], 1, v[122:123]
	v_cvt_pk_bf16_f32 v129, v124, v125
	v_lshl_add_u64 v[124:125], v[122:123], 0, v[0:1]
	s_mov_b64 s[6:7], -1
	s_and_b64 vcc, exec, s[50:51]
	v_lshl_add_u64 v[122:123], s[40:41], 0, v[148:149]
	global_store_dwordx4 v[124:125], v[126:129], off sc1
	s_cbranch_vccz .LBB0_242
	s_nop 0
	v_and_b32_e32 v126, 0x7cf, v146
	v_lshlrev_b32_e32 v126, 1, v126
	v_mov_b32_e32 v127, v1
	v_lshl_add_u64 v[126:127], v[122:123], 0, v[126:127]
	v_cvt_pk_bf16_f32 v128, v110, s0
	global_store_short v[126:127], v128, off sc1
	v_add_co_u32_e32 v128, vcc, 0x4000, v126
	v_cvt_pk_bf16_f32 v148, v106, s0
	s_nop 0
	v_addc_co_u32_e32 v129, vcc, 0, v127, vcc
	global_store_short v[128:129], v148, off sc1
	v_add_co_u32_e32 v128, vcc, 0x1000, v126
	v_cvt_pk_bf16_f32 v148, v111, s0
	s_nop 0
	v_addc_co_u32_e32 v129, vcc, 0, v127, vcc
	global_store_short v[128:129], v148, off sc1
	v_add_co_u32_e32 v128, vcc, 0x5000, v126
	v_cvt_pk_bf16_f32 v148, v107, s0
	s_nop 0
	v_addc_co_u32_e32 v129, vcc, 0, v127, vcc
	global_store_short v[128:129], v148, off sc1
	v_cvt_pk_bf16_f32 v148, v112, s0
	s_movk_i32 s0, 0x2000
	v_add_co_u32_e32 v128, vcc, s0, v126
	s_mov_b64 s[6:7], 0
	s_nop 0
	v_addc_co_u32_e32 v129, vcc, 0, v127, vcc
	global_store_short v[128:129], v148, off sc1
	v_add_co_u32_e32 v128, vcc, 0x6000, v126
	v_cvt_pk_bf16_f32 v148, v108, s0
	s_nop 0
	v_addc_co_u32_e32 v129, vcc, 0, v127, vcc
	global_store_short v[128:129], v148, off sc1
	v_add_co_u32_e32 v128, vcc, 0x3000, v126
	v_cvt_pk_bf16_f32 v148, v113, s0
	s_nop 0
	v_addc_co_u32_e32 v129, vcc, 0, v127, vcc
	v_add_co_u32_e32 v126, vcc, 0x7000, v126
	global_store_short v[128:129], v148, off sc1
	v_cvt_pk_bf16_f32 v128, v109, s0
	v_addc_co_u32_e32 v127, vcc, 0, v127, vcc
	global_store_short v[126:127], v128, off sc1
.LBB0_242:
	s_andn2_b64 vcc, exec, s[6:7]
	s_cbranch_vccnz .LBB0_244
	v_cvt_pk_bf16_f32 v110, v110, v111
	v_cvt_pk_bf16_f32 v111, v112, v113
	v_cvt_pk_bf16_f32 v112, v106, v107
	v_cvt_pk_bf16_f32 v113, v108, v109
	global_store_dwordx4 v[124:125], v[110:113], off offset:256 sc1
.LBB0_244:
	v_or_b32_e32 v108, 16, v146
	v_mov_b64_e32 v[106:107], s[34:35]
	v_mad_i64_i32 v[106:107], s[6:7], v108, s87, v[106:107]
	v_lshl_add_u64 v[106:107], s[4:5], 1, v[106:107]
	v_cndmask_b32_e64 v109, 0, 1, s[50:51]
	v_cvt_pk_bf16_f32 v110, v118, v119
	v_cvt_pk_bf16_f32 v111, v120, v121
	v_cvt_pk_bf16_f32 v112, v114, v115
	v_cvt_pk_bf16_f32 v113, v116, v117
	v_lshl_add_u64 v[106:107], v[106:107], 0, v[0:1]
	v_cmp_ne_u32_e64 s[38:39], 1, v109
	s_andn2_b64 vcc, exec, s[50:51]
	s_mov_b64 s[6:7], -1
	global_store_dwordx4 v[106:107], v[110:113], off sc1
	s_cbranch_vccnz .LBB0_246
	v_and_b32_e32 v108, 0x7df, v108
	v_lshlrev_b32_e32 v108, 1, v108
	v_mov_b32_e32 v109, v1
	v_lshl_add_u64 v[108:109], v[122:123], 0, v[108:109]
	v_cvt_pk_bf16_f32 v110, v94, s0
	global_store_short v[108:109], v110, off sc1
	v_add_co_u32_e32 v110, vcc, 0x4000, v108
	v_cvt_pk_bf16_f32 v112, v90, s0
	s_nop 0
	v_addc_co_u32_e32 v111, vcc, 0, v109, vcc
	global_store_short v[110:111], v112, off sc1
	v_add_co_u32_e32 v110, vcc, 0x1000, v108
	v_cvt_pk_bf16_f32 v112, v95, s0
	s_nop 0
	v_addc_co_u32_e32 v111, vcc, 0, v109, vcc
	global_store_short v[110:111], v112, off sc1
	v_add_co_u32_e32 v110, vcc, 0x5000, v108
	v_cvt_pk_bf16_f32 v112, v91, s0
	s_nop 0
	v_addc_co_u32_e32 v111, vcc, 0, v109, vcc
	global_store_short v[110:111], v112, off sc1
	v_cvt_pk_bf16_f32 v112, v96, s0
	s_movk_i32 s0, 0x2000
	v_add_co_u32_e32 v110, vcc, s0, v108
	s_mov_b64 s[6:7], 0
	s_nop 0
	v_addc_co_u32_e32 v111, vcc, 0, v109, vcc
	global_store_short v[110:111], v112, off sc1
	v_add_co_u32_e32 v110, vcc, 0x6000, v108
	v_cvt_pk_bf16_f32 v112, v92, s0
	s_nop 0
	v_addc_co_u32_e32 v111, vcc, 0, v109, vcc
	global_store_short v[110:111], v112, off sc1
	v_add_co_u32_e32 v110, vcc, 0x3000, v108
	v_cvt_pk_bf16_f32 v112, v97, s0
	s_nop 0
	v_addc_co_u32_e32 v111, vcc, 0, v109, vcc
	v_add_co_u32_e32 v108, vcc, 0x7000, v108
	global_store_short v[110:111], v112, off sc1
	v_cvt_pk_bf16_f32 v110, v93, s0
	v_addc_co_u32_e32 v109, vcc, 0, v109, vcc
	global_store_short v[108:109], v110, off sc1
.LBB0_246:
	s_andn2_b64 vcc, exec, s[6:7]
	s_cbranch_vccnz .LBB0_248
	v_cvt_pk_bf16_f32 v94, v94, v95
	v_cvt_pk_bf16_f32 v95, v96, v97
	v_cvt_pk_bf16_f32 v96, v90, v91
	v_cvt_pk_bf16_f32 v97, v92, v93
	global_store_dwordx4 v[106:107], v[94:97], off offset:256 sc1
; DI bf16_t f2bf(float a) { return (bf16_t)(pack2(a, 0.f) & 0xffffu); }
;   DI void operator()(const f32x4 (&acc)[2][2][4][2], const Unit& u, int wr, int wc, int fr, int fq) const {
;     ...
; #pragma unroll
;     for (int ai = 0; ai < 2; ++ai)
; #pragma unroll
;       for (int m = 0; m < 4; ++m) {
;         const int row = row0 + ai * HALF + m * 16;
;         *(u32x4*)(H + (size_t)row * HS + u.pn * BM + cl) = pack8(acc[ai][0][m][0], acc[ai][0][m][1]);
;         if (which < 0) {
;           *(u32x4*)(H + (size_t)row * HS + u.pn * BM + HALF + cl) = pack8(acc[ai][1][m][0], acc[ai][1][m][1]);
;         } else {
;           const int b = row >> 11, t = row & 2047;
;           bf16_t* vp = VT + ((size_t)((which * 8 + b) * 128 + cl)) * 2048 + t;
; #pragma unroll
;           for (int j = 0; j < 4; ++j) { vp[(size_t)j * 2048] = f2bf(acc[ai][1][m][0][j]); vp[(size_t)(4 + j) * 2048] = f2bf(acc[ai][1][m][1][j]); }
;         }
;       }
;   }
.LBB0_248:
	v_or_b32_e32 v92, 32, v146
	v_mov_b64_e32 v[90:91], s[34:35]
	v_mad_i64_i32 v[90:91], s[6:7], v92, s87, v[90:91]
	v_lshl_add_u64 v[90:91], s[4:5], 1, v[90:91]
	v_cvt_pk_bf16_f32 v94, v102, v103
	v_cvt_pk_bf16_f32 v95, v104, v105
	v_cvt_pk_bf16_f32 v96, v98, v99
	v_cvt_pk_bf16_f32 v97, v100, v101
	v_lshl_add_u64 v[90:91], v[90:91], 0, v[0:1]
	s_and_b64 vcc, exec, s[38:39]
	s_mov_b64 s[6:7], -1
	global_store_dwordx4 v[90:91], v[94:97], off sc1
	s_cbranch_vccnz .LBB0_250
	v_and_b32_e32 v92, 0x7ef, v92
	v_lshlrev_b32_e32 v92, 1, v92
	v_mov_b32_e32 v93, v1
	v_lshl_add_u64 v[92:93], v[122:123], 0, v[92:93]
	v_cvt_pk_bf16_f32 v94, v78, s0
	global_store_short v[92:93], v94, off sc1
	v_add_co_u32_e32 v94, vcc, 0x4000, v92
	v_cvt_pk_bf16_f32 v96, v74, s0
	s_nop 0
	v_addc_co_u32_e32 v95, vcc, 0, v93, vcc
	global_store_short v[94:95], v96, off sc1
	v_add_co_u32_e32 v94, vcc, 0x1000, v92
	v_cvt_pk_bf16_f32 v96, v79, s0
	s_nop 0
	v_addc_co_u32_e32 v95, vcc, 0, v93, vcc
	global_store_short v[94:95], v96, off sc1
	v_add_co_u32_e32 v94, vcc, 0x5000, v92
	v_cvt_pk_bf16_f32 v96, v75, s0
	s_nop 0
	v_addc_co_u32_e32 v95, vcc, 0, v93, vcc
	global_store_short v[94:95], v96, off sc1
	v_cvt_pk_bf16_f32 v96, v80, s0
	s_movk_i32 s0, 0x2000
	v_add_co_u32_e32 v94, vcc, s0, v92
	s_mov_b64 s[6:7], 0
	s_nop 0
	v_addc_co_u32_e32 v95, vcc, 0, v93, vcc
	global_store_short v[94:95], v96, off sc1
	v_add_co_u32_e32 v94, vcc, 0x6000, v92
	v_cvt_pk_bf16_f32 v96, v76, s0
	s_nop 0
	v_addc_co_u32_e32 v95, vcc, 0, v93, vcc
	global_store_short v[94:95], v96, off sc1
	v_add_co_u32_e32 v94, vcc, 0x3000, v92
	v_cvt_pk_bf16_f32 v96, v81, s0
	s_nop 0
	v_addc_co_u32_e32 v95, vcc, 0, v93, vcc
	v_add_co_u32_e32 v92, vcc, 0x7000, v92
	global_store_short v[94:95], v96, off sc1
	v_cvt_pk_bf16_f32 v94, v77, s0
	v_addc_co_u32_e32 v93, vcc, 0, v93, vcc
	global_store_short v[92:93], v94, off sc1
.LBB0_250:
	s_andn2_b64 vcc, exec, s[6:7]
	s_cbranch_vccnz .LBB0_252
	v_cvt_pk_bf16_f32 v78, v78, v79
	v_cvt_pk_bf16_f32 v79, v80, v81
	v_cvt_pk_bf16_f32 v80, v74, v75
	v_cvt_pk_bf16_f32 v81, v76, v77
	global_store_dwordx4 v[90:91], v[78:81], off offset:256 sc1
.LBB0_252:
	v_or_b32_e32 v76, 48, v146
	v_mov_b64_e32 v[74:75], s[34:35]
	v_mad_i64_i32 v[74:75], s[6:7], v76, s87, v[74:75]
	v_lshl_add_u64 v[74:75], s[4:5], 1, v[74:75]
	v_cvt_pk_bf16_f32 v78, v86, v87
	v_cvt_pk_bf16_f32 v79, v88, v89
	v_cvt_pk_bf16_f32 v80, v82, v83
	v_cvt_pk_bf16_f32 v81, v84, v85
	v_lshl_add_u64 v[74:75], v[74:75], 0, v[0:1]
	s_and_b64 vcc, exec, s[38:39]
	s_mov_b64 s[6:7], -1
	global_store_dwordx4 v[74:75], v[78:81], off sc1
	s_cbranch_vccnz .LBB0_254
	v_and_b32_e32 v76, 0x7ff, v76
	v_lshlrev_b32_e32 v76, 1, v76
	v_mov_b32_e32 v77, v1
	v_lshl_add_u64 v[76:77], v[122:123], 0, v[76:77]
	v_cvt_pk_bf16_f32 v78, v70, s0
	global_store_short v[76:77], v78, off sc1
	v_add_co_u32_e32 v78, vcc, 0x4000, v76
	v_cvt_pk_bf16_f32 v80, v66, s0
	s_nop 0
	v_addc_co_u32_e32 v79, vcc, 0, v77, vcc
	global_store_short v[78:79], v80, off sc1
	v_add_co_u32_e32 v78, vcc, 0x1000, v76
	v_cvt_pk_bf16_f32 v80, v71, s0
	s_nop 0
	v_addc_co_u32_e32 v79, vcc, 0, v77, vcc
	global_store_short v[78:79], v80, off sc1
	v_add_co_u32_e32 v78, vcc, 0x5000, v76
	v_cvt_pk_bf16_f32 v80, v67, s0
	s_nop 0
	v_addc_co_u32_e32 v79, vcc, 0, v77, vcc
	global_store_short v[78:79], v80, off sc1
	v_cvt_pk_bf16_f32 v80, v72, s0
	s_movk_i32 s0, 0x2000
	v_add_co_u32_e32 v78, vcc, s0, v76
	s_mov_b64 s[6:7], 0
	s_nop 0
	v_addc_co_u32_e32 v79, vcc, 0, v77, vcc
	global_store_short v[78:79], v80, off sc1
	v_add_co_u32_e32 v78, vcc, 0x6000, v76
	v_cvt_pk_bf16_f32 v80, v68, s0
	s_nop 0
	v_addc_co_u32_e32 v79, vcc, 0, v77, vcc
	global_store_short v[78:79], v80, off sc1
	v_add_co_u32_e32 v78, vcc, 0x3000, v76
	v_cvt_pk_bf16_f32 v80, v73, s0
	s_nop 0
	v_addc_co_u32_e32 v79, vcc, 0, v77, vcc
	v_add_co_u32_e32 v76, vcc, 0x7000, v76
	global_store_short v[78:79], v80, off sc1
	v_cvt_pk_bf16_f32 v78, v69, s0
	v_addc_co_u32_e32 v77, vcc, 0, v77, vcc
	global_store_short v[76:77], v78, off sc1
.LBB0_254:
	s_andn2_b64 vcc, exec, s[6:7]
	s_cbranch_vccnz .LBB0_256
	v_cvt_pk_bf16_f32 v70, v70, v71
	v_cvt_pk_bf16_f32 v71, v72, v73
	v_cvt_pk_bf16_f32 v72, v66, v67
	v_cvt_pk_bf16_f32 v73, v68, v69
	global_store_dwordx4 v[74:75], v[70:73], off offset:256 sc1
.LBB0_256:
	v_add_u32_e32 v66, 0x80, v146
	v_ashrrev_i32_e32 v67, 4, v66
	v_and_b32_e32 v67, 0xffffff80, v67
	v_add_u32_e32 v68, v147, v67
	v_cvt_pk_bf16_f32 v62, v62, v63
	v_cvt_pk_bf16_f32 v63, v64, v65
	v_cvt_pk_bf16_f32 v64, v58, v59
	v_mov_b64_e32 v[58:59], s[34:35]
	v_ashrrev_i32_e32 v69, 31, v68
	v_mad_i64_i32 v[58:59], s[6:7], v66, s87, v[58:59]
	v_lshlrev_b64 v[68:69], 12, v[68:69]
	v_lshl_add_u64 v[58:59], s[4:5], 1, v[58:59]
	v_cvt_pk_bf16_f32 v65, v60, v61
	v_lshl_add_u64 v[60:61], v[58:59], 0, v[0:1]
	s_mov_b64 s[6:7], -1
	s_and_b64 vcc, exec, s[38:39]
	v_lshl_add_u64 v[58:59], s[40:41], 0, v[68:69]
	global_store_dwordx4 v[60:61], v[62:65], off sc1
	s_cbranch_vccnz .LBB0_258
	s_nop 0
	v_and_b32_e32 v62, 0x7cf, v66
	v_lshlrev_b32_e32 v62, 1, v62
	v_mov_b32_e32 v63, v1
	v_lshl_add_u64 v[62:63], v[58:59], 0, v[62:63]
	v_cvt_pk_bf16_f32 v64, v46, s0
	global_store_short v[62:63], v64, off sc1
	v_add_co_u32_e32 v64, vcc, 0x4000, v62
	v_cvt_pk_bf16_f32 v66, v42, s0
	s_nop 0
	v_addc_co_u32_e32 v65, vcc, 0, v63, vcc
	global_store_short v[64:65], v66, off sc1
	v_add_co_u32_e32 v64, vcc, 0x1000, v62
	v_cvt_pk_bf16_f32 v66, v47, s0
	s_nop 0
	v_addc_co_u32_e32 v65, vcc, 0, v63, vcc
	global_store_short v[64:65], v66, off sc1
	v_add_co_u32_e32 v64, vcc, 0x5000, v62
	v_cvt_pk_bf16_f32 v66, v43, s0
	s_nop 0
	v_addc_co_u32_e32 v65, vcc, 0, v63, vcc
	global_store_short v[64:65], v66, off sc1
	v_cvt_pk_bf16_f32 v66, v48, s0
	s_movk_i32 s0, 0x2000
	v_add_co_u32_e32 v64, vcc, s0, v62
	s_mov_b64 s[6:7], 0
	s_nop 0
	v_addc_co_u32_e32 v65, vcc, 0, v63, vcc
	global_store_short v[64:65], v66, off sc1
	v_add_co_u32_e32 v64, vcc, 0x6000, v62
	v_cvt_pk_bf16_f32 v66, v44, s0
	s_nop 0
	v_addc_co_u32_e32 v65, vcc, 0, v63, vcc
	global_store_short v[64:65], v66, off sc1
	v_add_co_u32_e32 v64, vcc, 0x3000, v62
	v_cvt_pk_bf16_f32 v66, v49, s0
	s_nop 0
	v_addc_co_u32_e32 v65, vcc, 0, v63, vcc
	v_add_co_u32_e32 v62, vcc, 0x7000, v62
	global_store_short v[64:65], v66, off sc1
	v_cvt_pk_bf16_f32 v64, v45, s0
	v_addc_co_u32_e32 v63, vcc, 0, v63, vcc
	global_store_short v[62:63], v64, off sc1
; DI bf16_t f2bf(float a) { return (bf16_t)(pack2(a, 0.f) & 0xffffu); }
;   DI void operator()(const f32x4 (&acc)[2][2][4][2], const Unit& u, int wr, int wc, int fr, int fq) const {
;     ...
; #pragma unroll
;     for (int ai = 0; ai < 2; ++ai)
; #pragma unroll
;       for (int m = 0; m < 4; ++m) {
;         const int row = row0 + ai * HALF + m * 16;
;         *(u32x4*)(H + (size_t)row * HS + u.pn * BM + cl) = pack8(acc[ai][0][m][0], acc[ai][0][m][1]);
;         if (which < 0) {
;           *(u32x4*)(H + (size_t)row * HS + u.pn * BM + HALF + cl) = pack8(acc[ai][1][m][0], acc[ai][1][m][1]);
;         } else {
;           const int b = row >> 11, t = row & 2047;
;           bf16_t* vp = VT + ((size_t)((which * 8 + b) * 128 + cl)) * 2048 + t;
; #pragma unroll
;           for (int j = 0; j < 4; ++j) { vp[(size_t)j * 2048] = f2bf(acc[ai][1][m][0][j]); vp[(size_t)(4 + j) * 2048] = f2bf(acc[ai][1][m][1][j]); }
;         }
;       }
;   }
.LBB0_258:
	s_andn2_b64 vcc, exec, s[6:7]
	s_cbranch_vccnz .LBB0_260
	v_cvt_pk_bf16_f32 v46, v46, v47
	v_cvt_pk_bf16_f32 v47, v48, v49
	v_cvt_pk_bf16_f32 v48, v42, v43
	v_cvt_pk_bf16_f32 v49, v44, v45
	global_store_dwordx4 v[60:61], v[46:49], off offset:256 sc1
.LBB0_260:
	v_add_u32_e32 v44, 0x90, v146
	v_mov_b64_e32 v[42:43], s[34:35]
	v_mad_i64_i32 v[42:43], s[6:7], v44, s87, v[42:43]
	v_lshl_add_u64 v[42:43], s[4:5], 1, v[42:43]
	v_cvt_pk_bf16_f32 v46, v54, v55
	v_cvt_pk_bf16_f32 v47, v56, v57
	v_cvt_pk_bf16_f32 v48, v50, v51
	v_cvt_pk_bf16_f32 v49, v52, v53
	v_lshl_add_u64 v[42:43], v[42:43], 0, v[0:1]
	s_and_b64 vcc, exec, s[38:39]
	s_mov_b64 s[6:7], -1
	global_store_dwordx4 v[42:43], v[46:49], off sc1
	s_cbranch_vccnz .LBB0_262
	v_and_b32_e32 v44, 0x7df, v44
	v_lshlrev_b32_e32 v44, 1, v44
	v_mov_b32_e32 v45, v1
	v_lshl_add_u64 v[44:45], v[58:59], 0, v[44:45]
	v_cvt_pk_bf16_f32 v46, v30, s0
	global_store_short v[44:45], v46, off sc1
	v_add_co_u32_e32 v46, vcc, 0x4000, v44
	v_cvt_pk_bf16_f32 v48, v26, s0
	s_nop 0
	v_addc_co_u32_e32 v47, vcc, 0, v45, vcc
	global_store_short v[46:47], v48, off sc1
	v_add_co_u32_e32 v46, vcc, 0x1000, v44
	v_cvt_pk_bf16_f32 v48, v31, s0
	s_nop 0
	v_addc_co_u32_e32 v47, vcc, 0, v45, vcc
	global_store_short v[46:47], v48, off sc1
	v_add_co_u32_e32 v46, vcc, 0x5000, v44
	v_cvt_pk_bf16_f32 v48, v27, s0
	s_nop 0
	v_addc_co_u32_e32 v47, vcc, 0, v45, vcc
	global_store_short v[46:47], v48, off sc1
	v_cvt_pk_bf16_f32 v48, v32, s0
	s_movk_i32 s0, 0x2000
	v_add_co_u32_e32 v46, vcc, s0, v44
	s_mov_b64 s[6:7], 0
	s_nop 0
	v_addc_co_u32_e32 v47, vcc, 0, v45, vcc
	global_store_short v[46:47], v48, off sc1
	v_add_co_u32_e32 v46, vcc, 0x6000, v44
	v_cvt_pk_bf16_f32 v48, v28, s0
	s_nop 0
	v_addc_co_u32_e32 v47, vcc, 0, v45, vcc
	global_store_short v[46:47], v48, off sc1
	v_add_co_u32_e32 v46, vcc, 0x3000, v44
	v_cvt_pk_bf16_f32 v48, v33, s0
	s_nop 0
	v_addc_co_u32_e32 v47, vcc, 0, v45, vcc
	v_add_co_u32_e32 v44, vcc, 0x7000, v44
	global_store_short v[46:47], v48, off sc1
	v_cvt_pk_bf16_f32 v46, v29, s0
	v_addc_co_u32_e32 v45, vcc, 0, v45, vcc
	global_store_short v[44:45], v46, off sc1
.LBB0_262:
	s_andn2_b64 vcc, exec, s[6:7]
	s_cbranch_vccnz .LBB0_264
	v_cvt_pk_bf16_f32 v30, v30, v31
	v_cvt_pk_bf16_f32 v31, v32, v33
	v_cvt_pk_bf16_f32 v32, v26, v27
	v_cvt_pk_bf16_f32 v33, v28, v29
	global_store_dwordx4 v[42:43], v[30:33], off offset:256 sc1
.LBB0_264:
	v_add_u32_e32 v28, 0xa0, v146
	v_mov_b64_e32 v[26:27], s[34:35]
	v_mad_i64_i32 v[26:27], s[6:7], v28, s87, v[26:27]
	v_lshl_add_u64 v[26:27], s[4:5], 1, v[26:27]
	v_cvt_pk_bf16_f32 v30, v38, v39
	v_cvt_pk_bf16_f32 v31, v40, v41
	v_cvt_pk_bf16_f32 v32, v34, v35
	v_cvt_pk_bf16_f32 v33, v36, v37
	v_lshl_add_u64 v[26:27], v[26:27], 0, v[0:1]
	s_and_b64 vcc, exec, s[38:39]
	s_mov_b64 s[6:7], -1
	global_store_dwordx4 v[26:27], v[30:33], off sc1
	s_cbranch_vccnz .LBB0_266
	v_and_b32_e32 v28, 0x7ef, v28
	v_lshlrev_b32_e32 v28, 1, v28
	v_mov_b32_e32 v29, v1
	v_lshl_add_u64 v[28:29], v[58:59], 0, v[28:29]
	v_cvt_pk_bf16_f32 v30, v14, s0
	global_store_short v[28:29], v30, off sc1
	v_add_co_u32_e32 v30, vcc, 0x4000, v28
	v_cvt_pk_bf16_f32 v32, v10, s0
	s_nop 0
	v_addc_co_u32_e32 v31, vcc, 0, v29, vcc
	global_store_short v[30:31], v32, off sc1
	v_add_co_u32_e32 v30, vcc, 0x1000, v28
	v_cvt_pk_bf16_f32 v32, v15, s0
	s_nop 0
	v_addc_co_u32_e32 v31, vcc, 0, v29, vcc
	global_store_short v[30:31], v32, off sc1
	v_add_co_u32_e32 v30, vcc, 0x5000, v28
	v_cvt_pk_bf16_f32 v32, v11, s0
	s_nop 0
	v_addc_co_u32_e32 v31, vcc, 0, v29, vcc
	global_store_short v[30:31], v32, off sc1
	v_cvt_pk_bf16_f32 v32, v16, s0
	s_movk_i32 s0, 0x2000
	v_add_co_u32_e32 v30, vcc, s0, v28
	s_mov_b64 s[6:7], 0
	s_nop 0
	v_addc_co_u32_e32 v31, vcc, 0, v29, vcc
	global_store_short v[30:31], v32, off sc1
	v_add_co_u32_e32 v30, vcc, 0x6000, v28
	v_cvt_pk_bf16_f32 v32, v12, s0
	s_nop 0
	v_addc_co_u32_e32 v31, vcc, 0, v29, vcc
	global_store_short v[30:31], v32, off sc1
	v_add_co_u32_e32 v30, vcc, 0x3000, v28
	v_cvt_pk_bf16_f32 v32, v17, s0
	s_nop 0
	v_addc_co_u32_e32 v31, vcc, 0, v29, vcc
	v_add_co_u32_e32 v28, vcc, 0x7000, v28
	global_store_short v[30:31], v32, off sc1
	v_cvt_pk_bf16_f32 v30, v13, s0
	v_addc_co_u32_e32 v29, vcc, 0, v29, vcc
	global_store_short v[28:29], v30, off sc1
.LBB0_266:
	s_andn2_b64 vcc, exec, s[6:7]
	s_cbranch_vccnz .LBB0_268
	v_cvt_pk_bf16_f32 v14, v14, v15
	v_cvt_pk_bf16_f32 v15, v16, v17
	v_cvt_pk_bf16_f32 v16, v10, v11
	v_cvt_pk_bf16_f32 v17, v12, v13
	global_store_dwordx4 v[26:27], v[14:17], off offset:256 sc1
.LBB0_268:
	v_add_u32_e32 v12, 0xb0, v146
	v_mov_b64_e32 v[10:11], s[34:35]
	v_mad_i64_i32 v[10:11], s[6:7], v12, s87, v[10:11]
	v_lshl_add_u64 v[10:11], s[4:5], 1, v[10:11]
	v_cvt_pk_bf16_f32 v14, v22, v23
	v_cvt_pk_bf16_f32 v15, v24, v25
	v_cvt_pk_bf16_f32 v16, v18, v19
	v_cvt_pk_bf16_f32 v17, v20, v21
	v_lshl_add_u64 v[10:11], v[10:11], 0, v[0:1]
	s_and_b64 vcc, exec, s[38:39]
	s_mov_b64 s[4:5], -1
	global_store_dwordx4 v[10:11], v[14:17], off sc1
	s_cbranch_vccnz .LBB0_270
	v_and_b32_e32 v12, 0x7ff, v12
	v_lshlrev_b32_e32 v12, 1, v12
	v_mov_b32_e32 v13, v1
	v_lshl_add_u64 v[12:13], v[58:59], 0, v[12:13]
	v_cvt_pk_bf16_f32 v14, v6, s0
	global_store_short v[12:13], v14, off sc1
	v_add_co_u32_e32 v14, vcc, 0x4000, v12
	v_cvt_pk_bf16_f32 v16, v2, s0
	s_nop 0
	v_addc_co_u32_e32 v15, vcc, 0, v13, vcc
	global_store_short v[14:15], v16, off sc1
	v_add_co_u32_e32 v14, vcc, 0x1000, v12
	v_cvt_pk_bf16_f32 v16, v7, s0
	s_nop 0
	v_addc_co_u32_e32 v15, vcc, 0, v13, vcc
	global_store_short v[14:15], v16, off sc1
	v_add_co_u32_e32 v14, vcc, 0x5000, v12
	v_cvt_pk_bf16_f32 v16, v3, s0
	s_nop 0
	v_addc_co_u32_e32 v15, vcc, 0, v13, vcc
	global_store_short v[14:15], v16, off sc1
	v_cvt_pk_bf16_f32 v16, v8, s0
	s_movk_i32 s0, 0x2000
	v_add_co_u32_e32 v14, vcc, s0, v12
	s_mov_b64 s[4:5], 0
	s_nop 0
	v_addc_co_u32_e32 v15, vcc, 0, v13, vcc
	global_store_short v[14:15], v16, off sc1
	v_add_co_u32_e32 v14, vcc, 0x6000, v12
	v_cvt_pk_bf16_f32 v16, v4, s0
	s_nop 0
	v_addc_co_u32_e32 v15, vcc, 0, v13, vcc
	global_store_short v[14:15], v16, off sc1
	v_add_co_u32_e32 v14, vcc, 0x3000, v12
	v_cvt_pk_bf16_f32 v16, v9, s0
	s_nop 0
	v_addc_co_u32_e32 v15, vcc, 0, v13, vcc
	v_add_co_u32_e32 v12, vcc, 0x7000, v12
	global_store_short v[14:15], v16, off sc1
	v_cvt_pk_bf16_f32 v14, v5, s0
	v_addc_co_u32_e32 v13, vcc, 0, v13, vcc
	global_store_short v[12:13], v14, off sc1
.LBB0_270:
	s_andn2_b64 vcc, exec, s[4:5]
	s_cbranch_vccnz .LBB0_227
	v_cvt_pk_bf16_f32 v6, v6, v7
	v_cvt_pk_bf16_f32 v7, v8, v9
	v_cvt_pk_bf16_f32 v8, v2, v3
	v_cvt_pk_bf16_f32 v9, v4, v5
	global_store_dwordx4 v[10:11], v[6:9], off offset:256 sc1
	s_branch .LBB0_227

; __device__ __forceinline__ unsigned xb_ld(unsigned* p)              { return __hip_atomic_load(p, __ATOMIC_RELAXED, __HIP_MEMORY_SCOPE_AGENT); }
; __device__ __forceinline__ unsigned xb_add(unsigned* p, unsigned v) { return __hip_atomic_fetch_add(p, v, __ATOMIC_RELAXED, __HIP_MEMORY_SCOPE_AGENT); }
; #define XB_SPIN(cond, bar) do { unsigned _sp = 0; while (cond) { __builtin_amdgcn_s_sleep(1); \
;     if ((++_sp & 255u) == 0u) { if (xb_ld(&(bar)[XB_TMO])) break; if (_sp > XB_SPIN_CAP) { atomicAdd(&(bar)[XB_TMO], 1u); break; } } } } while (0)
; __device__ __forceinline__ void xcd_barrier(const XcdBarrier& b) {
;     ...
;         if (old + 1u == (gen + 1u) * nloc) {
;             __builtin_amdgcn_fence(__ATOMIC_RELEASE, "agent");
;             asm volatile("s_waitcnt vmcnt(0)" ::: "memory");
;             const unsigned og = xb_add(&bar[XB_TOP], 1u);
;             const unsigned tg = og / nx;
;             if (og + 1u == (tg + 1u) * nx) xb_add(&bar[XB_TOPGEN], 1u);
;             else XB_SPIN(xb_ld(&bar[XB_TOPGEN]) == tg, bar);
;             __builtin_amdgcn_fence(__ATOMIC_ACQUIRE, "agent");
.LBB0_303:
	s_andn2_saveexec_b64 s[6:7], s[34:35]
	s_cbranch_execz .LBB0_319
	v_mov_b32_e32 v2, s4
	v_add_co_u32_e32 v2, vcc, 0x3000, v2
	v_mov_b32_e32 v3, s5
	buffer_inv sc1
	s_waitcnt vmcnt(0)
	v_addc_co_u32_e32 v3, vcc, 0, v3, vcc
	flat_atomic_add v2, v[2:3], v223 offset:1024 sc0
	v_cvt_f32_u32_e32 v3, v0
	v_sub_u32_e32 v4, 0, v0
	s_add_u32 s34, s4, 0x3500
	s_addc_u32 s35, s5, 0
	v_rcp_iflag_f32_e32 v3, v3
	s_nop 0
	v_mul_f32_e32 v3, 0x4f7ffffe, v3
	v_cvt_u32_f32_e32 v3, v3
	v_mul_lo_u32 v4, v4, v3
	v_mul_hi_u32 v4, v3, v4
	v_add_u32_e32 v3, v3, v4
	s_waitcnt vmcnt(0) lgkmcnt(0)
	v_mul_hi_u32 v3, v2, v3
	v_mul_lo_u32 v4, v3, v0
	v_sub_u32_e32 v4, v2, v4
	v_cmp_ge_u32_e32 vcc, v4, v0
	v_add_u32_e32 v5, 1, v3
	s_nop 0
	v_cndmask_b32_e32 v3, v3, v5, vcc
	v_sub_u32_e32 v5, v4, v0
	v_cndmask_b32_e32 v4, v4, v5, vcc
	v_cmp_ge_u32_e32 vcc, v4, v0
	v_add_u32_e32 v4, 1, v3
	v_add_u32_e32 v5, 1, v2
	v_cndmask_b32_e32 v4, v3, v4, vcc
	v_mad_u64_u32 v[2:3], s[6:7], v0, v4, v[0:1]
	v_cmp_ne_u32_e32 vcc, v5, v2
	s_mov_b64 s[6:7], -1
	v_mov_b64_e32 v[2:3], s[34:35]
	s_and_saveexec_b64 s[36:37], vcc
	s_cbranch_execz .LBB0_316
	v_mov_b64_e32 v[2:3], s[34:35]
	flat_load_dword v0, v[2:3] sc1
	s_mov_b64 s[6:7], 0
	s_waitcnt vmcnt(0) lgkmcnt(0)
	v_cmp_eq_u32_e32 vcc, v0, v4
	s_and_saveexec_b64 s[22:23], vcc
	s_cbranch_execz .LBB0_315
	s_add_u32 s20, s4, 0x200
	s_addc_u32 s21, s5, 0
	s_mov_b32 s46, 1
	s_mov_b64 s[4:5], 0
	s_branch .LBB0_308

; template <int MODE> ...
;     ...
;   while (j <= jhi) {
;     __syncthreads();
;     *(uint4*)(Ks + lr * LDT + lc) = k0;
;     *(uint4*)(Vs + lr * LDT + lc) = v0;
;     __syncthreads();
.LBB0_523:
	s_cmp_ge_u32 s8, s22
	s_cselect_b64 s[4:5], -1, 0
	s_and_b64 vcc, exec, s[4:5]
	s_barrier
	s_waitcnt vmcnt(1)
	ds_write_b128 v146, v[128:131]
	s_waitcnt vmcnt(0)
	v_and_b32_e32 v249, 1, v201
	v_lshlrev_b32_e32 v249, 3, v249
	v_sub_u32_e32 v249, v146, v249
	v_add_u32_e32 v249, 0x2400, v249
	ds_write2_b64 v249, v[132:133], v[134:135] offset1:2
	s_waitcnt lgkmcnt(0)
	s_barrier
	s_cbranch_vccnz .LBB0_525
	s_add_i32 s6, s2, 64
	v_add_u32_e32 v0, s2, v151
	s_movk_i32 s0, 0x1e00
	v_mad_i64_i32 v[2:3], s[12:13], v0, s0, v[136:137]
	s_ashr_i32 s7, s6, 31
	global_load_dwordx4 v[128:131], v[2:3], off offset:2048
	v_lshl_add_u64 v[2:3], s[6:7], 1, v[138:139]
	global_load_dwordx4 v[132:135], v[2:3], off

; template <int MODE> ...
;     ...
;   while (j <= jhi) {
;     __syncthreads();
;     *(uint4*)(Ks + lr * LDT + lc) = k0;
;     *(uint4*)(Vs + lr * LDT + lc) = v0;
;     __syncthreads();
.LBB0_607:
	s_max_i32 s0, s10, s22
	s_add_i32 s8, s0, 1
	s_mov_b32 s6, s10
	s_waitcnt lgkmcnt(0)
	s_barrier
	s_waitcnt vmcnt(1)
	ds_write_b128 v237, v[192:195]
	s_waitcnt vmcnt(0)
	v_and_b32_e32 v249, 1, v201
	v_lshlrev_b32_e32 v249, 3, v249
	v_sub_u32_e32 v249, v237, v249
	v_add_u32_e32 v249, 0x2400, v249
	ds_write2_b64 v249, v[196:197], v[198:199] offset1:2
	s_waitcnt lgkmcnt(0)
	s_barrier
	s_branch .LBB0_609

; template <int MODE> ...
;     ...
;   while (j <= jhi) {
;     __syncthreads();
;     *(uint4*)(Ks + lr * LDT + lc) = k0;
;     *(uint4*)(Vs + lr * LDT + lc) = v0;
;     __syncthreads();
.LBB0_628:
	s_cmp_ge_u32 s7, s22
	s_waitcnt lgkmcnt(0)
	s_barrier
	s_waitcnt vmcnt(1)
	ds_write_b128 v174, v[162:165]
	s_waitcnt vmcnt(0)
	v_and_b32_e32 v249, 1, v201
	v_lshlrev_b32_e32 v249, 3, v249
	v_sub_u32_e32 v249, v174, v249
	v_add_u32_e32 v249, 0x2400, v249
	ds_write2_b64 v249, v[166:167], v[168:169] offset1:2
	s_waitcnt lgkmcnt(0)
	s_barrier
	s_cbranch_scc1 .LBB0_630
	v_readlane_b32 s2, v252, 52
	s_movk_i32 s0, 0x1e00
	v_readlane_b32 s3, v252, 53
	v_add_u32_e32 v0, s2, v128
	v_mad_i64_i32 v[2:3], s[0:1], v0, s0, v[172:173]
	global_load_dwordx4 v[162:165], v[2:3], off offset:1536
	v_lshl_add_u64 v[2:3], s[2:3], 1, v[170:171]
	global_load_dwordx4 v[166:169], v[2:3], off

; template <int MODE> ...
;     ...
;   while (j <= jhi) {
;     __syncthreads();
;     *(uint4*)(Ks + lr * LDT + lc) = k0;
;     *(uint4*)(Vs + lr * LDT + lc) = v0;
;     __syncthreads();
.LBB0_646:
	s_cmp_gt_i32 s20, s9
	s_cselect_b64 s[4:5], -1, 0
	s_and_b64 vcc, exec, s[4:5]
	s_barrier
	s_waitcnt vmcnt(1)
	ds_write_b128 v132, v[106:109]
	s_waitcnt vmcnt(0)
	v_and_b32_e32 v249, 1, v201
	v_lshlrev_b32_e32 v249, 3, v249
	v_sub_u32_e32 v249, v132, v249
	v_add_u32_e32 v249, 0x2400, v249
	ds_write2_b64 v249, v[114:115], v[116:117] offset1:2
	s_waitcnt lgkmcnt(0)
	s_barrier
	s_cbranch_vccnz .LBB0_648
	s_add_i32 s6, s2, 64
	v_add_u32_e32 v0, s2, v137
	v_mad_i64_i32 v[34:35], s[22:23], v0, s1, v[126:127]
	s_ashr_i32 s7, s6, 31
	global_load_dwordx4 v[106:109], v[34:35], off
	v_lshl_add_u64 v[34:35], s[6:7], 1, v[128:129]
	global_load_dwordx4 v[114:117], v[34:35], off

; DI float bf2f(bf16_t u) { return __uint_as_float(((unsigned)u) << 16); }
; DI int bidx() { int b = blockIdx.x; asm volatile("" : "+s"(b)); return b; }
; DI float wave_sum_fast(float v) { v = fdpp_add(v, 0); v = fdpp_add(v, 1); v = fdpp_add(v, 2); v = fdpp_add(v, 3); v = xor16_sum(v); return xor32_sum(v); }
; DI void rwkv_post(const Params& p, int l) {
;     ...
;   for (int it = bidx(); it < NTOK / 16; it += gridDim.x) {
;     float y[8], v[8], z[8], bo[8];
; #pragma unroll
;     for (int q = 0; q < 8; ++q) {
;       const size_t m = (size_t)it * 16 + sub * 8 + q;
;       const int b = (int)(m >> 11), t = (int)(m & 2047);
;       y[q] = bf2f(yr[m * 256 + hd * 64 + lane]);
;       v[q] = bf2f(pr[((size_t)((b * 4 + hd) * 2048 + t)) * 384 + 3 * 64 + lane]);
;       z[q] = bf2f(hw[m * HS + C_CZ + hd * 64 + lane]);
;       bo[q] = bon[m * 4 + hd];
;     }
; #pragma unroll
;     for (int q = 0; q < 8; ++q) {
;       const size_t m = (size_t)it * 16 + sub * 8 + q;
;       const float mean = wave_sum_fast(y[q]) * (1.f / 64.f);
.LBB0_862:
	s_lshl_b32 s0, s2, 4
	v_mov_b32_e32 v99, 0
	v_add_u32_e32 v98, s0, v2
	s_movk_i32 s0, 0x7f8
	s_mov_b32 s41, 0
	v_lshrrev_b32_e32 v118, 9, v98
	v_lshlrev_b64 v[88:89], 9, v[98:99]
	v_and_or_b32 v118, v118, s21, v30
	v_lshl_add_u64 v[90:91], v[98:99], 4, v[8:9]
	v_lshl_add_u64 v[88:89], v[88:89], 0, v[4:5]
	v_lshlrev_b32_e32 v118, 11, v118
	v_mov_b64_e32 v[96:97], s[8:9]
	v_and_or_b32 v118, v98, s0, v118
	v_mad_u64_u32 v[96:97], s[0:1], v98, s12, v[96:97]
	v_mad_i64_i32 v[92:93], s[0:1], v118, s22, v[6:7]
	v_mov_b32_e32 v11, v1
	v_lshl_add_u64 v[96:97], v[96:97], 0, v[0:1]
	s_movk_i32 s40, 0x1200
	v_lshl_add_u64 v[96:97], v[96:97], 0, v[10:11]
	v_lshl_add_u64 v[94:95], v[92:93], 0, s[40:41]
	s_mov_b32 s40, 0x1b00
	v_lshl_add_u64 v[72:73], v[96:97], 0, s[40:41]
	s_mov_b32 s40, 0x3900
	v_lshl_add_u64 v[74:75], v[96:97], 0, s[40:41]
	s_mov_b32 s40, 0x5700
	v_lshl_add_u64 v[76:77], v[96:97], 0, s[40:41]
	s_mov_b32 s40, 0x7500
	v_lshl_add_u64 v[78:79], v[96:97], 0, s[40:41]
	s_mov_b32 s40, 0x9300
	v_lshl_add_u64 v[80:81], v[96:97], 0, s[40:41]
	s_mov_b32 s40, 0xb100
	v_lshl_add_u64 v[82:83], v[96:97], 0, s[40:41]
	s_mov_b32 s40, 0xcf00
	v_lshl_add_u64 v[84:85], v[96:97], 0, s[40:41]
	s_mov_b32 s40, 0xed00
	v_lshl_add_u64 v[86:87], v[96:97], 0, s[40:41]
	global_load_ushort v40, v[88:89], off
	global_load_ushort v41, v[88:89], off offset:512
	global_load_ushort v42, v[88:89], off offset:1024
	global_load_ushort v43, v[88:89], off offset:1536
	global_load_ushort v44, v[88:89], off offset:2048
	global_load_ushort v45, v[88:89], off offset:2560
	global_load_ushort v46, v[88:89], off offset:3072
	global_load_ushort v47, v[88:89], off offset:3584
	global_load_ushort v48, v[92:93], off
	global_load_ushort v49, v[92:93], off offset:768
	global_load_ushort v50, v[92:93], off offset:1536
	global_load_ushort v51, v[92:93], off offset:2304
	global_load_ushort v52, v[92:93], off offset:3072
	global_load_ushort v53, v[92:93], off offset:3840
	global_load_ushort v54, v[94:95], off
	global_load_ushort v55, v[94:95], off offset:768
	global_load_ushort v56, v[72:73], off
	global_load_ushort v57, v[74:75], off
	global_load_ushort v58, v[76:77], off
	global_load_ushort v59, v[78:79], off
	global_load_ushort v60, v[80:81], off
	global_load_ushort v61, v[82:83], off
	global_load_ushort v62, v[84:85], off
	global_load_ushort v63, v[86:87], off
	global_load_dword v64, v[90:91], off
	global_load_dword v65, v[90:91], off offset:16
	global_load_dword v66, v[90:91], off offset:32
	global_load_dword v67, v[90:91], off offset:48
	global_load_dword v68, v[90:91], off offset:64
	global_load_dword v69, v[90:91], off offset:80
	global_load_dword v70, v[90:91], off offset:96
	global_load_dword v71, v[90:91], off offset:112
	v_mov_b32_e32 v116, 0x3a27c5ac
	s_waitcnt vmcnt(0)
	v_lshlrev_b32_e32 v40, 16, v40
	v_lshlrev_b32_e32 v41, 16, v41
	v_lshlrev_b32_e32 v42, 16, v42
	v_lshlrev_b32_e32 v43, 16, v43
	v_lshlrev_b32_e32 v44, 16, v44
	v_lshlrev_b32_e32 v45, 16, v45
	v_lshlrev_b32_e32 v46, 16, v46
	v_lshlrev_b32_e32 v47, 16, v47
	v_lshlrev_b32_e32 v48, 16, v48
	v_lshlrev_b32_e32 v49, 16, v49
	v_lshlrev_b32_e32 v50, 16, v50
	v_lshlrev_b32_e32 v51, 16, v51
	v_lshlrev_b32_e32 v52, 16, v52
	v_lshlrev_b32_e32 v53, 16, v53
	v_lshlrev_b32_e32 v54, 16, v54
	v_lshlrev_b32_e32 v55, 16, v55
	v_lshlrev_b32_e32 v56, 16, v56
	v_lshlrev_b32_e32 v57, 16, v57
	v_lshlrev_b32_e32 v58, 16, v58
	v_lshlrev_b32_e32 v59, 16, v59
	v_lshlrev_b32_e32 v60, 16, v60
	v_lshlrev_b32_e32 v61, 16, v61
	v_lshlrev_b32_e32 v62, 16, v62
	v_lshlrev_b32_e32 v63, 16, v63
	v_add_f32_dpp v100, v40, v40 quad_perm:[1,0,3,2] row_mask:0xf bank_mask:0xf bound_ctrl:1
	v_add_f32_dpp v101, v41, v41 quad_perm:[1,0,3,2] row_mask:0xf bank_mask:0xf bound_ctrl:1
	v_add_f32_dpp v102, v42, v42 quad_perm:[1,0,3,2] row_mask:0xf bank_mask:0xf bound_ctrl:1
	v_add_f32_dpp v103, v43, v43 quad_perm:[1,0,3,2] row_mask:0xf bank_mask:0xf bound_ctrl:1
	v_add_f32_dpp v104, v44, v44 quad_perm:[1,0,3,2] row_mask:0xf bank_mask:0xf bound_ctrl:1
	v_add_f32_dpp v105, v45, v45 quad_perm:[1,0,3,2] row_mask:0xf bank_mask:0xf bound_ctrl:1
	v_add_f32_dpp v106, v46, v46 quad_perm:[1,0,3,2] row_mask:0xf bank_mask:0xf bound_ctrl:1
	v_add_f32_dpp v107, v47, v47 quad_perm:[1,0,3,2] row_mask:0xf bank_mask:0xf bound_ctrl:1
	v_add_f32_dpp v100, v100, v100 quad_perm:[2,3,0,1] row_mask:0xf bank_mask:0xf bound_ctrl:1
	v_add_f32_dpp v101, v101, v101 quad_perm:[2,3,0,1] row_mask:0xf bank_mask:0xf bound_ctrl:1
	v_add_f32_dpp v102, v102, v102 quad_perm:[2,3,0,1] row_mask:0xf bank_mask:0xf bound_ctrl:1
	v_add_f32_dpp v103, v103, v103 quad_perm:[2,3,0,1] row_mask:0xf bank_mask:0xf bound_ctrl:1
	v_add_f32_dpp v104, v104, v104 quad_perm:[2,3,0,1] row_mask:0xf bank_mask:0xf bound_ctrl:1
	v_add_f32_dpp v105, v105, v105 quad_perm:[2,3,0,1] row_mask:0xf bank_mask:0xf bound_ctrl:1
	v_add_f32_dpp v106, v106, v106 quad_perm:[2,3,0,1] row_mask:0xf bank_mask:0xf bound_ctrl:1
	v_add_f32_dpp v107, v107, v107 quad_perm:[2,3,0,1] row_mask:0xf bank_mask:0xf bound_ctrl:1
	v_add_f32_dpp v100, v100, v100 row_half_mirror row_mask:0xf bank_mask:0xf bound_ctrl:1
	v_add_f32_dpp v101, v101, v101 row_half_mirror row_mask:0xf bank_mask:0xf bound_ctrl:1
	v_add_f32_dpp v102, v102, v102 row_half_mirror row_mask:0xf bank_mask:0xf bound_ctrl:1
	v_add_f32_dpp v103, v103, v103 row_half_mirror row_mask:0xf bank_mask:0xf bound_ctrl:1
	v_add_f32_dpp v104, v104, v104 row_half_mirror row_mask:0xf bank_mask:0xf bound_ctrl:1
	v_add_f32_dpp v105, v105, v105 row_half_mirror row_mask:0xf bank_mask:0xf bound_ctrl:1
	v_add_f32_dpp v106, v106, v106 row_half_mirror row_mask:0xf bank_mask:0xf bound_ctrl:1
; DI float wave_sum_fast(float v) { v = fdpp_add(v, 0); v = fdpp_add(v, 1); v = fdpp_add(v, 2); v = fdpp_add(v, 3); v = xor16_sum(v); return xor32_sum(v); }
; DI void rwkv_post(const Params& p, int l) {
;     ...
;       const float mean = wave_sum_fast(y[q]) * (1.f / 64.f);
;       const float dlt = y[q] - mean;
;       const float var = wave_sum_fast(dlt * dlt) * (1.f / 64.f);
;       float o = dlt * rsqrtf(var + 64e-5f) * lw + lb + bo[q] * v[q];
	v_add_f32_dpp v107, v107, v107 row_half_mirror row_mask:0xf bank_mask:0xf bound_ctrl:1
	v_add_f32_dpp v100, v100, v100 row_mirror row_mask:0xf bank_mask:0xf bound_ctrl:1
	v_add_f32_dpp v101, v101, v101 row_mirror row_mask:0xf bank_mask:0xf bound_ctrl:1
	v_add_f32_dpp v102, v102, v102 row_mirror row_mask:0xf bank_mask:0xf bound_ctrl:1
	v_add_f32_dpp v103, v103, v103 row_mirror row_mask:0xf bank_mask:0xf bound_ctrl:1
	v_add_f32_dpp v104, v104, v104 row_mirror row_mask:0xf bank_mask:0xf bound_ctrl:1
	v_add_f32_dpp v105, v105, v105 row_mirror row_mask:0xf bank_mask:0xf bound_ctrl:1
	v_add_f32_dpp v106, v106, v106 row_mirror row_mask:0xf bank_mask:0xf bound_ctrl:1
	v_add_f32_dpp v107, v107, v107 row_mirror row_mask:0xf bank_mask:0xf bound_ctrl:1
	v_mov_b32_e32 v108, v100
	v_mov_b32_e32 v109, v101
	v_mov_b32_e32 v110, v102
	v_mov_b32_e32 v111, v103
	v_mov_b32_e32 v112, v104
	v_mov_b32_e32 v113, v105
	v_mov_b32_e32 v114, v106
	v_mov_b32_e32 v115, v107
	v_permlane16_swap_b32_e32 v100, v108
	v_permlane16_swap_b32_e32 v101, v109
	v_permlane16_swap_b32_e32 v102, v110
	v_permlane16_swap_b32_e32 v103, v111
	v_permlane16_swap_b32_e32 v104, v112
	v_permlane16_swap_b32_e32 v105, v113
	v_permlane16_swap_b32_e32 v106, v114
	v_permlane16_swap_b32_e32 v107, v115
	v_add_f32_e32 v100, v100, v108
	v_add_f32_e32 v101, v101, v109
	v_add_f32_e32 v102, v102, v110
	v_add_f32_e32 v103, v103, v111
	v_add_f32_e32 v104, v104, v112
	v_add_f32_e32 v105, v105, v113
	v_add_f32_e32 v106, v106, v114
	v_add_f32_e32 v107, v107, v115
	v_mov_b32_e32 v108, v100
	v_mov_b32_e32 v109, v101
	v_mov_b32_e32 v110, v102
	v_mov_b32_e32 v111, v103
	v_mov_b32_e32 v112, v104
	v_mov_b32_e32 v113, v105
	v_mov_b32_e32 v114, v106
	v_mov_b32_e32 v115, v107
	v_permlane32_swap_b32_e32 v100, v108
	v_permlane32_swap_b32_e32 v101, v109
	v_permlane32_swap_b32_e32 v102, v110
	v_permlane32_swap_b32_e32 v103, v111
	v_permlane32_swap_b32_e32 v104, v112
	v_permlane32_swap_b32_e32 v105, v113
	v_permlane32_swap_b32_e32 v106, v114
	v_permlane32_swap_b32_e32 v107, v115
	v_add_f32_e32 v100, v100, v108
	v_add_f32_e32 v101, v101, v109
	v_add_f32_e32 v102, v102, v110
	v_add_f32_e32 v103, v103, v111
	v_add_f32_e32 v104, v104, v112
	v_add_f32_e32 v105, v105, v113
	v_add_f32_e32 v106, v106, v114
	v_add_f32_e32 v107, v107, v115
	v_fmac_f32_e32 v40, 0xbc800000, v100
	v_fmac_f32_e32 v41, 0xbc800000, v101
	v_fmac_f32_e32 v42, 0xbc800000, v102
	v_fmac_f32_e32 v43, 0xbc800000, v103
	v_fmac_f32_e32 v44, 0xbc800000, v104
	v_fmac_f32_e32 v45, 0xbc800000, v105
	v_fmac_f32_e32 v46, 0xbc800000, v106
	v_fmac_f32_e32 v47, 0xbc800000, v107
	v_mul_f32_e32 v108, v40, v40
	v_mul_f32_e32 v109, v41, v41
	v_mul_f32_e32 v110, v42, v42
	v_mul_f32_e32 v111, v43, v43
	v_mul_f32_e32 v112, v44, v44
	v_mul_f32_e32 v113, v45, v45
	v_mul_f32_e32 v114, v46, v46
	v_mul_f32_e32 v115, v47, v47
	v_add_f32_dpp v100, v108, v108 quad_perm:[1,0,3,2] row_mask:0xf bank_mask:0xf bound_ctrl:1
	v_add_f32_dpp v101, v109, v109 quad_perm:[1,0,3,2] row_mask:0xf bank_mask:0xf bound_ctrl:1
	v_add_f32_dpp v102, v110, v110 quad_perm:[1,0,3,2] row_mask:0xf bank_mask:0xf bound_ctrl:1
	v_add_f32_dpp v103, v111, v111 quad_perm:[1,0,3,2] row_mask:0xf bank_mask:0xf bound_ctrl:1
	v_add_f32_dpp v104, v112, v112 quad_perm:[1,0,3,2] row_mask:0xf bank_mask:0xf bound_ctrl:1
	v_add_f32_dpp v105, v113, v113 quad_perm:[1,0,3,2] row_mask:0xf bank_mask:0xf bound_ctrl:1
	v_add_f32_dpp v106, v114, v114 quad_perm:[1,0,3,2] row_mask:0xf bank_mask:0xf bound_ctrl:1
	v_add_f32_dpp v107, v115, v115 quad_perm:[1,0,3,2] row_mask:0xf bank_mask:0xf bound_ctrl:1
	v_add_f32_dpp v100, v100, v100 quad_perm:[2,3,0,1] row_mask:0xf bank_mask:0xf bound_ctrl:1
	v_add_f32_dpp v101, v101, v101 quad_perm:[2,3,0,1] row_mask:0xf bank_mask:0xf bound_ctrl:1
	v_add_f32_dpp v102, v102, v102 quad_perm:[2,3,0,1] row_mask:0xf bank_mask:0xf bound_ctrl:1
	v_add_f32_dpp v103, v103, v103 quad_perm:[2,3,0,1] row_mask:0xf bank_mask:0xf bound_ctrl:1
	v_add_f32_dpp v104, v104, v104 quad_perm:[2,3,0,1] row_mask:0xf bank_mask:0xf bound_ctrl:1
	v_add_f32_dpp v105, v105, v105 quad_perm:[2,3,0,1] row_mask:0xf bank_mask:0xf bound_ctrl:1
	v_add_f32_dpp v106, v106, v106 quad_perm:[2,3,0,1] row_mask:0xf bank_mask:0xf bound_ctrl:1
	v_add_f32_dpp v107, v107, v107 quad_perm:[2,3,0,1] row_mask:0xf bank_mask:0xf bound_ctrl:1
	v_add_f32_dpp v100, v100, v100 row_half_mirror row_mask:0xf bank_mask:0xf bound_ctrl:1
	v_add_f32_dpp v101, v101, v101 row_half_mirror row_mask:0xf bank_mask:0xf bound_ctrl:1
	v_add_f32_dpp v102, v102, v102 row_half_mirror row_mask:0xf bank_mask:0xf bound_ctrl:1
	v_add_f32_dpp v103, v103, v103 row_half_mirror row_mask:0xf bank_mask:0xf bound_ctrl:1
	v_add_f32_dpp v104, v104, v104 row_half_mirror row_mask:0xf bank_mask:0xf bound_ctrl:1
	v_add_f32_dpp v105, v105, v105 row_half_mirror row_mask:0xf bank_mask:0xf bound_ctrl:1
	v_add_f32_dpp v106, v106, v106 row_half_mirror row_mask:0xf bank_mask:0xf bound_ctrl:1
	v_add_f32_dpp v107, v107, v107 row_half_mirror row_mask:0xf bank_mask:0xf bound_ctrl:1
	v_add_f32_dpp v100, v100, v100 row_mirror row_mask:0xf bank_mask:0xf bound_ctrl:1
	v_add_f32_dpp v101, v101, v101 row_mirror row_mask:0xf bank_mask:0xf bound_ctrl:1
	v_add_f32_dpp v102, v102, v102 row_mirror row_mask:0xf bank_mask:0xf bound_ctrl:1
	v_add_f32_dpp v103, v103, v103 row_mirror row_mask:0xf bank_mask:0xf bound_ctrl:1
; DI bf16_t f2bf(float a) { return (bf16_t)(pack2(a, 0.f) & 0xffffu); }
; DI float siluf_(float x) { return x * __builtin_amdgcn_rcpf(1.f + __expf(-x)); }
; DI float wave_sum_fast(float v) { v = fdpp_add(v, 0); v = fdpp_add(v, 1); v = fdpp_add(v, 2); v = fdpp_add(v, 3); v = xor16_sum(v); return xor32_sum(v); }
; DI void rwkv_post(const Params& p, int l) {
;     ...
;       const float dlt = y[q] - mean;
;       const float var = wave_sum_fast(dlt * dlt) * (1.f / 64.f);
;       float o = dlt * rsqrtf(var + 64e-5f) * lw + lb + bo[q] * v[q];
;       o *= siluf_(z[q]);
;       hw[m * HS + C_CZ + hd * 64 + lane] = f2bf(o);
;     }
;   }
	v_add_f32_dpp v104, v104, v104 row_mirror row_mask:0xf bank_mask:0xf bound_ctrl:1
	v_add_f32_dpp v105, v105, v105 row_mirror row_mask:0xf bank_mask:0xf bound_ctrl:1
	v_add_f32_dpp v106, v106, v106 row_mirror row_mask:0xf bank_mask:0xf bound_ctrl:1
	v_add_f32_dpp v107, v107, v107 row_mirror row_mask:0xf bank_mask:0xf bound_ctrl:1
	v_mov_b32_e32 v108, v100
	v_mov_b32_e32 v109, v101
	v_mov_b32_e32 v110, v102
	v_mov_b32_e32 v111, v103
	v_mov_b32_e32 v112, v104
	v_mov_b32_e32 v113, v105
	v_mov_b32_e32 v114, v106
	v_mov_b32_e32 v115, v107
	v_permlane16_swap_b32_e32 v100, v108
	v_permlane16_swap_b32_e32 v101, v109
	v_permlane16_swap_b32_e32 v102, v110
	v_permlane16_swap_b32_e32 v103, v111
	v_permlane16_swap_b32_e32 v104, v112
	v_permlane16_swap_b32_e32 v105, v113
	v_permlane16_swap_b32_e32 v106, v114
	v_permlane16_swap_b32_e32 v107, v115
	v_add_f32_e32 v100, v100, v108
	v_add_f32_e32 v101, v101, v109
	v_add_f32_e32 v102, v102, v110
	v_add_f32_e32 v103, v103, v111
	v_add_f32_e32 v104, v104, v112
	v_add_f32_e32 v105, v105, v113
	v_add_f32_e32 v106, v106, v114
	v_add_f32_e32 v107, v107, v115
	v_mov_b32_e32 v108, v100
	v_mov_b32_e32 v109, v101
	v_mov_b32_e32 v110, v102
	v_mov_b32_e32 v111, v103
	v_mov_b32_e32 v112, v104
	v_mov_b32_e32 v113, v105
	v_mov_b32_e32 v114, v106
	v_mov_b32_e32 v115, v107
	v_permlane32_swap_b32_e32 v100, v108
	v_permlane32_swap_b32_e32 v101, v109
	v_permlane32_swap_b32_e32 v102, v110
	v_permlane32_swap_b32_e32 v103, v111
	v_permlane32_swap_b32_e32 v104, v112
	v_permlane32_swap_b32_e32 v105, v113
	v_permlane32_swap_b32_e32 v106, v114
	v_permlane32_swap_b32_e32 v107, v115
	v_add_f32_e32 v100, v100, v108
	v_add_f32_e32 v101, v101, v109
	v_add_f32_e32 v102, v102, v110
	v_add_f32_e32 v103, v103, v111
	v_add_f32_e32 v104, v104, v112
	v_add_f32_e32 v105, v105, v113
	v_add_f32_e32 v106, v106, v114
	v_add_f32_e32 v107, v107, v115
	v_fmamk_f32 v100, v100, 0x3c800000, v116
	v_fmamk_f32 v101, v101, 0x3c800000, v116
	v_fmamk_f32 v102, v102, 0x3c800000, v116
	v_fmamk_f32 v103, v103, 0x3c800000, v116
	v_fmamk_f32 v104, v104, 0x3c800000, v116
	v_fmamk_f32 v105, v105, 0x3c800000, v116
	v_fmamk_f32 v106, v106, 0x3c800000, v116
	v_fmamk_f32 v107, v107, 0x3c800000, v116
	v_rsq_f32_e32 v100, v100
	v_rsq_f32_e32 v101, v101
	v_rsq_f32_e32 v102, v102
	v_rsq_f32_e32 v103, v103
	v_rsq_f32_e32 v104, v104
	v_rsq_f32_e32 v105, v105
	v_rsq_f32_e32 v106, v106
	v_rsq_f32_e32 v107, v107
	v_mul_f32_e32 v108, 0xbfb8aa3b, v56
	v_mul_f32_e32 v109, 0xbfb8aa3b, v57
	v_mul_f32_e32 v110, 0xbfb8aa3b, v58
	v_mul_f32_e32 v111, 0xbfb8aa3b, v59
	v_mul_f32_e32 v112, 0xbfb8aa3b, v60
	v_mul_f32_e32 v113, 0xbfb8aa3b, v61
	v_mul_f32_e32 v114, 0xbfb8aa3b, v62
	v_mul_f32_e32 v115, 0xbfb8aa3b, v63
	v_exp_f32_e32 v108, v108
	v_exp_f32_e32 v109, v109
	v_exp_f32_e32 v110, v110
	v_exp_f32_e32 v111, v111
	v_exp_f32_e32 v112, v112
	v_exp_f32_e32 v113, v113
	v_exp_f32_e32 v114, v114
	v_exp_f32_e32 v115, v115
	v_mul_f32_e32 v40, v40, v100
	v_mul_f32_e32 v41, v41, v101
	v_mul_f32_e32 v42, v42, v102
	v_mul_f32_e32 v43, v43, v103
	v_mul_f32_e32 v44, v44, v104
	v_mul_f32_e32 v45, v45, v105
	v_mul_f32_e32 v46, v46, v106
	v_mul_f32_e32 v47, v47, v107
	v_add_f32_e32 v108, 1.0, v108
	v_add_f32_e32 v109, 1.0, v109
	v_add_f32_e32 v110, 1.0, v110
	v_add_f32_e32 v111, 1.0, v111
	v_add_f32_e32 v112, 1.0, v112
	v_add_f32_e32 v113, 1.0, v113
	v_add_f32_e32 v114, 1.0, v114
	v_add_f32_e32 v115, 1.0, v115
	v_rcp_f32_e32 v108, v108
	v_rcp_f32_e32 v109, v109
	v_rcp_f32_e32 v110, v110
	v_rcp_f32_e32 v111, v111
	v_rcp_f32_e32 v112, v112
	v_rcp_f32_e32 v113, v113
	v_rcp_f32_e32 v114, v114
	v_rcp_f32_e32 v115, v115
	v_fma_f32 v40, v31, v40, v32
	v_fma_f32 v41, v31, v41, v32
	v_fma_f32 v42, v31, v42, v32
	v_fma_f32 v43, v31, v43, v32
	v_fma_f32 v44, v31, v44, v32
	v_fma_f32 v45, v31, v45, v32
	v_fma_f32 v46, v31, v46, v32
	v_fma_f32 v47, v31, v47, v32
	v_fmac_f32_e32 v40, v64, v48
	v_fmac_f32_e32 v41, v65, v49
	v_fmac_f32_e32 v42, v66, v50
	v_fmac_f32_e32 v43, v67, v51
	v_fmac_f32_e32 v44, v68, v52
	v_fmac_f32_e32 v45, v69, v53
	v_fmac_f32_e32 v46, v70, v54
	v_fmac_f32_e32 v47, v71, v55
	v_mul_f32_e32 v108, v108, v56
	v_mul_f32_e32 v109, v109, v57
	v_mul_f32_e32 v110, v110, v58
	v_mul_f32_e32 v111, v111, v59
	v_mul_f32_e32 v112, v112, v60
	v_mul_f32_e32 v113, v113, v61
	v_mul_f32_e32 v114, v114, v62
	v_mul_f32_e32 v115, v115, v63
	v_mul_f32_e32 v40, v108, v40
	v_mul_f32_e32 v41, v109, v41
	v_mul_f32_e32 v42, v110, v42
	v_mul_f32_e32 v43, v111, v43
	v_mul_f32_e32 v44, v112, v44
	v_mul_f32_e32 v45, v113, v45
	v_mul_f32_e32 v46, v114, v46
	v_mul_f32_e32 v47, v115, v47
	v_cvt_pk_bf16_f32 v40, v40, v40
	v_cvt_pk_bf16_f32 v41, v41, v41
	v_cvt_pk_bf16_f32 v42, v42, v42
	v_cvt_pk_bf16_f32 v43, v43, v43
	v_cvt_pk_bf16_f32 v44, v44, v44
	v_cvt_pk_bf16_f32 v45, v45, v45
	v_cvt_pk_bf16_f32 v46, v46, v46
	v_cvt_pk_bf16_f32 v47, v47, v47
	global_store_short v[72:73], v40, off sc1
	global_store_short v[74:75], v41, off sc1
	global_store_short v[76:77], v42, off sc1
	global_store_short v[78:79], v43, off sc1
	global_store_short v[80:81], v44, off sc1
	global_store_short v[82:83], v45, off sc1
	global_store_short v[84:85], v46, off sc1
	global_store_short v[86:87], v47, off sc1
	s_add_i32 s2, s2, s4
	s_cmpk_lt_i32 s2, 0x400
	s_cbranch_scc1 .LBB0_862
	s_movk_i32 s87, 0x1e00

; __device__ __forceinline__ unsigned xb_ld(unsigned* p)              { return __hip_atomic_load(p, __ATOMIC_RELAXED, __HIP_MEMORY_SCOPE_AGENT); }
; __device__ __forceinline__ unsigned xb_add(unsigned* p, unsigned v) { return __hip_atomic_fetch_add(p, v, __ATOMIC_RELAXED, __HIP_MEMORY_SCOPE_AGENT); }
; #define XB_SPIN(cond, bar) do { unsigned _sp = 0; while (cond) { __builtin_amdgcn_s_sleep(1); \
;     if ((++_sp & 255u) == 0u) { if (xb_ld(&(bar)[XB_TMO])) break; if (_sp > XB_SPIN_CAP) { atomicAdd(&(bar)[XB_TMO], 1u); break; } } } } while (0)
; __device__ __forceinline__ void xcd_barrier(const XcdBarrier& b) {
;     ...
;         if (old + 1u == (gen + 1u) * nloc) {
;             __builtin_amdgcn_fence(__ATOMIC_RELEASE, "agent");
;             asm volatile("s_waitcnt vmcnt(0)" ::: "memory");
;             const unsigned og = xb_add(&bar[XB_TOP], 1u);
;             const unsigned tg = og / nx;
;             if (og + 1u == (tg + 1u) * nx) xb_add(&bar[XB_TOPGEN], 1u);
;             else XB_SPIN(xb_ld(&bar[XB_TOPGEN]) == tg, bar);
;             __builtin_amdgcn_fence(__ATOMIC_ACQUIRE, "agent");
.LBB0_892:
	s_andn2_saveexec_b64 s[0:1], s[8:9]
	s_cbranch_execz .LBB0_908
	v_mov_b32_e32 v2, s4
	v_add_co_u32_e32 v2, vcc, 0x3000, v2
	v_mov_b32_e32 v3, s5
	buffer_inv sc1
	s_waitcnt vmcnt(0)
	v_addc_co_u32_e32 v3, vcc, 0, v3, vcc
	flat_atomic_add v2, v[2:3], v223 offset:1024 sc0
	v_cvt_f32_u32_e32 v3, v0
	v_sub_u32_e32 v4, 0, v0
	s_add_u32 s8, s4, 0x3500
	s_addc_u32 s9, s5, 0
	v_rcp_iflag_f32_e32 v3, v3
	s_mov_b64 s[6:7], -1
	v_mul_f32_e32 v3, 0x4f7ffffe, v3
	v_cvt_u32_f32_e32 v3, v3
	v_mul_lo_u32 v4, v4, v3
	v_mul_hi_u32 v4, v3, v4
	v_add_u32_e32 v3, v3, v4
	s_waitcnt vmcnt(0) lgkmcnt(0)
	v_mul_hi_u32 v3, v2, v3
	v_mul_lo_u32 v4, v3, v0
	v_sub_u32_e32 v4, v2, v4
	v_cmp_ge_u32_e32 vcc, v4, v0
	v_add_u32_e32 v5, 1, v3
	s_nop 0
	v_cndmask_b32_e32 v3, v3, v5, vcc
	v_sub_u32_e32 v5, v4, v0
	v_cndmask_b32_e32 v4, v4, v5, vcc
	v_cmp_ge_u32_e32 vcc, v4, v0
	v_add_u32_e32 v4, 1, v3
	v_add_u32_e32 v5, 1, v2
	v_cndmask_b32_e32 v4, v3, v4, vcc
	v_mad_u64_u32 v[2:3], s[0:1], v0, v4, v[0:1]
	v_cmp_ne_u32_e32 vcc, v5, v2
	v_mov_b64_e32 v[2:3], s[8:9]
	s_and_saveexec_b64 s[12:13], vcc
	s_cbranch_execz .LBB0_905
	v_mov_b64_e32 v[2:3], s[8:9]
	flat_load_dword v0, v[2:3] sc1
	s_mov_b64 s[6:7], 0
	s_waitcnt vmcnt(0) lgkmcnt(0)
	v_cmp_eq_u32_e32 vcc, v0, v4
	s_and_saveexec_b64 s[22:23], vcc
	s_cbranch_execz .LBB0_904
	s_add_u32 s20, s4, 0x200
	s_addc_u32 s21, s5, 0
	s_mov_b32 s42, 1
	s_mov_b64 s[4:5], 0
	s_branch .LBB0_897

; #define PG8_STAGE(bufoff, gbase, voff) do { _Pragma("unroll") for (int _i = 0; _i < 2; ++_i) \
;         __builtin_amdgcn_global_load_lds((const unsigned*)((const char*)(gbase) + (voff)[_i]), (LAS unsigned*)(lds + (bufoff) + ldsw + _i * 8192), 16, 0, 0); } while (0)
; #define PG8_LDA(dst, b, h) do { _Pragma("unroll") for (int m = 0; m < 4; ++m) _Pragma("unroll") for (int k = 0; k < 2; ++k) dst[m][k] = *(const LAS bf16x8*)(lds + PG8_SA(b, h) + aoff + m * 2048 + k * 1024); } while (0)
; #define PG8_LDB(dst, b, h) do { _Pragma("unroll") for (int n = 0; n < 2; ++n) _Pragma("unroll") for (int k = 0; k < 2; ++k) dst[n][k] = *(const LAS bf16x8*)(lds + PG8_SB(b, h) + boff + n * 2048 + k * 1024); } while (0)
; #define PG8_MMA(ai, bj, At, Bt) do { __builtin_amdgcn_s_setprio(1); _Pragma("unroll") for (int m = 0; m < 4; ++m) _Pragma("unroll") for (int n = 0; n < 2; ++n) _Pragma("unroll") for (int k = 0; k < 2; ++k) \
;         acc[ai][bj][m][n] = __builtin_amdgcn_mfma_f32_16x16x32_bf16(Bt[n][k], At[m][k], acc[ai][bj][m][n], 0, 0, 0); __builtin_amdgcn_s_setprio(0); } while (0)
; #define PG8_WAIT_V(n) asm volatile("s_waitcnt vmcnt(" #n ")" ::: "memory")
; #define PG8_WAIT_L(n) asm volatile("s_waitcnt lgkmcnt(" #n ")" ::: "memory")
; #define PG8_BAR __builtin_amdgcn_s_barrier()
; #define PG8_SCHED __builtin_amdgcn_sched_barrier(0)
; #define PG8_WAIT_V(n) asm volatile("s_waitcnt vmcnt(" #n ")" ::: "memory")
; template <class Epi, class Sched>
; DI void gemm_phase(LAS unsigned char* lds, const Gemm g, const Sched& S, const Epi& E) {
;     ...
;             PG8_LDB(B0, 0, 0); PG8_SCHED; PG8_LDA(At, 0, 0); PG8_STAGE(PG8_SA(1, 1), a1 + hstepA, voffA);
;             PG8_WAIT_L(8); PG8_BAR; PG8_WAIT_L(0); PG8_MMA(0, 0, At, B0); PG8_BAR; PG8_SCHED;
;             PG8_LDB(B1, 0, 1); PG8_STAGE(PG8_SB(0, 0), b2, voffB);
;             PG8_BAR; PG8_WAIT_L(0); PG8_MMA(0, 1, At, B1); PG8_BAR;
;             PG8_LDA(At, 0, 1); PG8_STAGE(PG8_SA(0, 0), a2, voffA);
;             PG8_BAR; PG8_WAIT_L(0); PG8_MMA(1, 0, At, B0); PG8_BAR; PG8_SCHED;
;             PG8_STAGE(PG8_SB(0, 1), b2 + hstepB, voffB);
;             PG8_WAIT_V(6); PG8_BAR; PG8_MMA(1, 1, At, B1); PG8_BAR;
;             PG8_LDB(B0, 1, 0); PG8_SCHED; PG8_LDA(At, 1, 0); PG8_STAGE(PG8_SA(0, 1), a2 + hstepA, voffA);
;             PG8_WAIT_L(8); PG8_BAR; PG8_WAIT_L(0); PG8_MMA(0, 0, At, B0); PG8_BAR; PG8_SCHED;
.LBB0_1039:
	s_add_u32 s0, s42, 0xfffc0080
	s_addc_u32 s1, s43, -1
	s_add_i32 s11, 0, 0x10000
	s_cmp_eq_u32 s60, 12
	s_cselect_b32 s47, s6, s1
	s_cselect_b32 s46, s7, s0
	s_cselect_b32 s45, s9, s59
	s_cselect_b32 s44, s13, s58
	v_lshl_add_u64 v[188:189], s[42:43], 0, v[134:135]
	s_add_i32 m0, s51, 0xc000
	ds_read_b128 v[156:159], v147
	ds_read_b128 v[160:163], v147 offset:1024
	ds_read_b128 v[164:167], v147 offset:2048
	ds_read_b128 v[168:171], v147 offset:3072
	ds_read_b128 v[172:175], v147 offset:4096
	ds_read_b128 v[176:179], v147 offset:5120
	ds_read_b128 v[180:183], v147 offset:6144
	ds_read_b128 v[184:187], v147 offset:7168
	global_load_lds_dwordx4 v[188:189], off
	v_lshl_add_u64 v[188:189], s[42:43], 0, v[132:133]
	s_add_i32 m0, s51, 0xe000
	s_nop 0
	global_load_lds_dwordx4 v[188:189], off
	s_waitcnt lgkmcnt(8)
	s_barrier
	s_waitcnt lgkmcnt(0)
	s_setprio 1
	s_waitcnt lgkmcnt(0)
	v_mfma_f32_16x16x32_bf16 v[126:129], v[136:139], v[156:159], v[126:129]
	v_mfma_f32_16x16x32_bf16 v[122:125], v[148:151], v[156:159], v[122:125]
	v_mfma_f32_16x16x32_bf16 v[118:121], v[136:139], v[164:167], v[118:121]
	v_mfma_f32_16x16x32_bf16 v[114:117], v[148:151], v[164:167], v[114:117]
	v_mfma_f32_16x16x32_bf16 v[94:97], v[136:139], v[172:175], v[94:97]
	v_mfma_f32_16x16x32_bf16 v[90:93], v[148:151], v[172:175], v[90:93]
	v_mfma_f32_16x16x32_bf16 v[86:89], v[136:139], v[180:183], v[86:89]
	v_mfma_f32_16x16x32_bf16 v[82:85], v[148:151], v[180:183], v[82:85]
	v_mfma_f32_16x16x32_bf16 v[126:129], v[140:143], v[160:163], v[126:129]
	v_mfma_f32_16x16x32_bf16 v[122:125], v[152:155], v[160:163], v[122:125]
	v_mfma_f32_16x16x32_bf16 v[118:121], v[140:143], v[168:171], v[118:121]
	v_mfma_f32_16x16x32_bf16 v[114:117], v[152:155], v[168:171], v[114:117]
	v_mfma_f32_16x16x32_bf16 v[94:97], v[140:143], v[176:179], v[94:97]
	v_mfma_f32_16x16x32_bf16 v[90:93], v[152:155], v[176:179], v[90:93]
	v_mfma_f32_16x16x32_bf16 v[86:89], v[140:143], v[184:187], v[86:89]
	v_mfma_f32_16x16x32_bf16 v[82:85], v[152:155], v[184:187], v[82:85]
	s_setprio 0
	s_barrier
	s_add_i32 s61, 0, 0x14000
	s_add_i32 s0, s11, s50
	v_add_u32_e32 v210, s61, v145
	v_lshl_add_u64 v[214:215], s[44:45], 0, v[0:1]
	s_mov_b32 m0, s0
	ds_read_b128 v[188:191], v210
	ds_read_b128 v[192:195], v210 offset:1024
	ds_read_b128 v[196:199], v210 offset:2048
	ds_read_b128 v[210:213], v210 offset:3072
	global_load_lds_dwordx4 v[214:215], off
	v_lshl_add_u64 v[216:217], s[44:45], 0, v[130:131]
	s_add_i32 m0, s0, 0x2000
	s_nop 0
	global_load_lds_dwordx4 v[216:217], off
	s_barrier
	s_waitcnt lgkmcnt(0)
	s_setprio 1
	s_waitcnt lgkmcnt(0)
	v_mfma_f32_16x16x32_bf16 v[110:113], v[188:191], v[156:159], v[110:113]
	v_mfma_f32_16x16x32_bf16 v[106:109], v[196:199], v[156:159], v[106:109]
	v_mfma_f32_16x16x32_bf16 v[102:105], v[188:191], v[164:167], v[102:105]
	v_mfma_f32_16x16x32_bf16 v[98:101], v[196:199], v[164:167], v[98:101]
	v_mfma_f32_16x16x32_bf16 v[78:81], v[188:191], v[172:175], v[78:81]
	v_mfma_f32_16x16x32_bf16 v[74:77], v[196:199], v[172:175], v[74:77]
	v_mfma_f32_16x16x32_bf16 v[70:73], v[188:191], v[180:183], v[70:73]
	v_mfma_f32_16x16x32_bf16 v[66:69], v[196:199], v[180:183], v[66:69]
	v_mfma_f32_16x16x32_bf16 v[110:113], v[192:195], v[160:163], v[110:113]
	v_mfma_f32_16x16x32_bf16 v[106:109], v[210:213], v[160:163], v[106:109]
	v_mfma_f32_16x16x32_bf16 v[102:105], v[192:195], v[168:171], v[102:105]
	v_mfma_f32_16x16x32_bf16 v[98:101], v[210:213], v[168:171], v[98:101]
	v_mfma_f32_16x16x32_bf16 v[78:81], v[192:195], v[176:179], v[78:81]
	v_mfma_f32_16x16x32_bf16 v[74:77], v[210:213], v[176:179], v[74:77]
	v_mfma_f32_16x16x32_bf16 v[70:73], v[192:195], v[184:187], v[70:73]
	v_mfma_f32_16x16x32_bf16 v[66:69], v[210:213], v[184:187], v[66:69]
	s_setprio 0
	s_mov_b32 m0, s51
	v_lshl_add_u64 v[218:219], s[46:47], 0, v[0:1]
	s_barrier
	ds_read_b128 v[156:159], v147 offset:16384
	ds_read_b128 v[160:163], v147 offset:17408
	ds_read_b128 v[164:167], v147 offset:18432
	ds_read_b128 v[168:171], v147 offset:19456
	ds_read_b128 v[172:175], v147 offset:20480
	ds_read_b128 v[176:179], v147 offset:21504
	ds_read_b128 v[180:183], v147 offset:22528
	ds_read_b128 v[184:187], v147 offset:23552
	global_load_lds_dwordx4 v[218:219], off
	v_lshl_add_u64 v[220:221], s[46:47], 0, v[130:131]
	s_mov_b32 m0, s52
	s_nop 0
	global_load_lds_dwordx4 v[220:221], off
	s_waitcnt vmcnt(10)
	s_barrier
	s_waitcnt lgkmcnt(0)
	s_setprio 1
	s_waitcnt lgkmcnt(0)
	v_mfma_f32_16x16x32_bf16 v[62:65], v[136:139], v[156:159], v[62:65]
	v_mfma_f32_16x16x32_bf16 v[58:61], v[148:151], v[156:159], v[58:61]
	v_mfma_f32_16x16x32_bf16 v[54:57], v[136:139], v[164:167], v[54:57]
	v_mfma_f32_16x16x32_bf16 v[50:53], v[148:151], v[164:167], v[50:53]
	v_mfma_f32_16x16x32_bf16 v[30:33], v[136:139], v[172:175], v[30:33]
	v_mfma_f32_16x16x32_bf16 v[26:29], v[148:151], v[172:175], v[26:29]
	v_mfma_f32_16x16x32_bf16 v[22:25], v[136:139], v[180:183], v[22:25]
	v_mfma_f32_16x16x32_bf16 v[18:21], v[148:151], v[180:183], v[18:21]
	v_mfma_f32_16x16x32_bf16 v[62:65], v[140:143], v[160:163], v[62:65]
	v_mfma_f32_16x16x32_bf16 v[58:61], v[152:155], v[160:163], v[58:61]
	v_mfma_f32_16x16x32_bf16 v[54:57], v[140:143], v[168:171], v[54:57]
	v_mfma_f32_16x16x32_bf16 v[50:53], v[152:155], v[168:171], v[50:53]
	v_mfma_f32_16x16x32_bf16 v[30:33], v[140:143], v[176:179], v[30:33]
	v_mfma_f32_16x16x32_bf16 v[26:29], v[152:155], v[176:179], v[26:29]
	v_mfma_f32_16x16x32_bf16 v[22:25], v[140:143], v[184:187], v[22:25]
	v_mfma_f32_16x16x32_bf16 v[18:21], v[152:155], v[184:187], v[18:21]
	s_setprio 0
	s_barrier
; #define PG8_STAGE(bufoff, gbase, voff) do { _Pragma("unroll") for (int _i = 0; _i < 2; ++_i) \
;         __builtin_amdgcn_global_load_lds((const unsigned*)((const char*)(gbase) + (voff)[_i]), (LAS unsigned*)(lds + (bufoff) + ldsw + _i * 8192), 16, 0, 0); } while (0)
; #define PG8_LDA(dst, b, h) do { _Pragma("unroll") for (int m = 0; m < 4; ++m) _Pragma("unroll") for (int k = 0; k < 2; ++k) dst[m][k] = *(const LAS bf16x8*)(lds + PG8_SA(b, h) + aoff + m * 2048 + k * 1024); } while (0)
; #define PG8_LDB(dst, b, h) do { _Pragma("unroll") for (int n = 0; n < 2; ++n) _Pragma("unroll") for (int k = 0; k < 2; ++k) dst[n][k] = *(const LAS bf16x8*)(lds + PG8_SB(b, h) + boff + n * 2048 + k * 1024); } while (0)
; #define PG8_MMA(ai, bj, At, Bt) do { __builtin_amdgcn_s_setprio(1); _Pragma("unroll") for (int m = 0; m < 4; ++m) _Pragma("unroll") for (int n = 0; n < 2; ++n) _Pragma("unroll") for (int k = 0; k < 2; ++k) \
;         acc[ai][bj][m][n] = __builtin_amdgcn_mfma_f32_16x16x32_bf16(Bt[n][k], At[m][k], acc[ai][bj][m][n], 0, 0, 0); __builtin_amdgcn_s_setprio(0); } while (0)
; #define PG8_WAIT_V(n) asm volatile("s_waitcnt vmcnt(" #n ")" ::: "memory")
; #define PG8_WAIT_L(n) asm volatile("s_waitcnt lgkmcnt(" #n ")" ::: "memory")
; #define PG8_BAR __builtin_amdgcn_s_barrier()
; #define PG8_SCHED __builtin_amdgcn_sched_barrier(0)
; #define PG8_LDA(dst, b, h) do { _Pragma("unroll") for (int m = 0; m < 4; ++m) _Pragma("unroll") for (int k = 0; k < 2; ++k) dst[m][k] = *(const LAS bf16x8*)(lds + PG8_SA(b, h) + aoff + m * 2048 + k * 1024); } while (0)
; #define PG8_WAIT_V(n) asm volatile("s_waitcnt vmcnt(" #n ")" ::: "memory")
; template <class Epi, class Sched>
; DI void gemm_phase(LAS unsigned char* lds, const Gemm g, const Sched& S, const Epi& E) {
;     ...
;             PG8_STAGE(PG8_SB(0, 1), b2 + hstepB, voffB);
;             PG8_WAIT_V(6); PG8_BAR; PG8_MMA(1, 1, At, B1); PG8_BAR;
;             PG8_LDB(B0, 1, 0); PG8_SCHED; PG8_LDA(At, 1, 0); PG8_STAGE(PG8_SA(0, 1), a2 + hstepA, voffA);
;             PG8_WAIT_L(8); PG8_BAR; PG8_WAIT_L(0); PG8_MMA(0, 0, At, B0); PG8_BAR; PG8_SCHED;
;             PG8_LDB(B1, 1, 1); PG8_STAGE(PG8_SB(1, 0), b3, voffB);
;             PG8_BAR; PG8_WAIT_L(0); PG8_MMA(0, 1, At, B1); PG8_BAR;
;             PG8_LDA(At, 1, 1); PG8_STAGE(PG8_SA(1, 0), a3, voffA);
;             PG8_BAR; PG8_WAIT_L(0); PG8_MMA(1, 0, At, B0); PG8_BAR; PG8_SCHED;
	s_add_u32 s0, s44, 0x40000
	s_addc_u32 s1, s45, 0
	s_add_i32 s11, s61, s50
	v_lshl_add_u64 v[136:137], s[0:1], 0, v[0:1]
	s_mov_b32 m0, s11
	s_nop 0
	global_load_lds_dwordx4 v[136:137], off
	v_lshl_add_u64 v[136:137], s[0:1], 0, v[130:131]
	s_add_i32 m0, s11, 0x2000
	s_nop 0
	global_load_lds_dwordx4 v[136:137], off
	v_add_u32_e32 v152, 0x18000, v145
	ds_read_b128 v[136:139], v152
	ds_read_b128 v[140:143], v152 offset:1024
	ds_read_b128 v[148:151], v152 offset:2048
	ds_read_b128 v[152:155], v152 offset:3072
	s_waitcnt vmcnt(6)
	s_barrier
	s_setprio 1
	v_mfma_f32_16x16x32_bf16 v[46:49], v[188:191], v[156:159], v[46:49]
	v_mfma_f32_16x16x32_bf16 v[42:45], v[196:199], v[156:159], v[42:45]
	v_mfma_f32_16x16x32_bf16 v[38:41], v[188:191], v[164:167], v[38:41]
	v_mfma_f32_16x16x32_bf16 v[34:37], v[196:199], v[164:167], v[34:37]
	v_mfma_f32_16x16x32_bf16 v[14:17], v[188:191], v[172:175], v[14:17]
	v_mfma_f32_16x16x32_bf16 v[10:13], v[196:199], v[172:175], v[10:13]
	v_mfma_f32_16x16x32_bf16 v[6:9], v[188:191], v[180:183], v[6:9]
	v_mfma_f32_16x16x32_bf16 v[2:5], v[196:199], v[180:183], v[2:5]
	v_mfma_f32_16x16x32_bf16 v[46:49], v[192:195], v[160:163], v[46:49]
	v_mfma_f32_16x16x32_bf16 v[42:45], v[210:213], v[160:163], v[42:45]
	v_mfma_f32_16x16x32_bf16 v[38:41], v[192:195], v[168:171], v[38:41]
	v_mfma_f32_16x16x32_bf16 v[34:37], v[210:213], v[168:171], v[34:37]
	v_mfma_f32_16x16x32_bf16 v[14:17], v[192:195], v[176:179], v[14:17]
	v_mfma_f32_16x16x32_bf16 v[10:13], v[210:213], v[176:179], v[10:13]
	v_mfma_f32_16x16x32_bf16 v[6:9], v[192:195], v[184:187], v[6:9]
	v_mfma_f32_16x16x32_bf16 v[2:5], v[210:213], v[184:187], v[2:5]
	s_setprio 0
	s_add_i32 s11, 0, 0x18000
	s_barrier
	s_add_u32 s0, s46, 0x40000
	s_addc_u32 s1, s47, 0
	s_mov_b32 m0, s53
	v_lshl_add_u64 v[188:189], s[0:1], 0, v[0:1]
	ds_read_b128 v[156:159], v147 offset:32768
	ds_read_b128 v[160:163], v147 offset:33792
	ds_read_b128 v[164:167], v147 offset:34816
	ds_read_b128 v[168:171], v147 offset:35840
	ds_read_b128 v[172:175], v147 offset:36864
	ds_read_b128 v[176:179], v147 offset:37888
	ds_read_b128 v[180:183], v147 offset:38912
	ds_read_b128 v[184:187], v147 offset:39936
	global_load_lds_dwordx4 v[188:189], off
	v_lshl_add_u64 v[188:189], s[0:1], 0, v[130:131]
	s_mov_b32 m0, s54
	s_nop 0
	global_load_lds_dwordx4 v[188:189], off
	s_waitcnt lgkmcnt(8)
	s_barrier
	s_waitcnt lgkmcnt(0)
	s_setprio 1
	s_waitcnt lgkmcnt(0)
	v_mfma_f32_16x16x32_bf16 v[126:129], v[136:139], v[156:159], v[126:129]
	v_mfma_f32_16x16x32_bf16 v[122:125], v[148:151], v[156:159], v[122:125]
	v_mfma_f32_16x16x32_bf16 v[118:121], v[136:139], v[164:167], v[118:121]
	v_mfma_f32_16x16x32_bf16 v[114:117], v[148:151], v[164:167], v[114:117]
	v_mfma_f32_16x16x32_bf16 v[94:97], v[136:139], v[172:175], v[94:97]
	v_mfma_f32_16x16x32_bf16 v[90:93], v[148:151], v[172:175], v[90:93]
	v_mfma_f32_16x16x32_bf16 v[86:89], v[136:139], v[180:183], v[86:89]
	v_mfma_f32_16x16x32_bf16 v[82:85], v[148:151], v[180:183], v[82:85]
	v_mfma_f32_16x16x32_bf16 v[126:129], v[140:143], v[160:163], v[126:129]
	v_mfma_f32_16x16x32_bf16 v[122:125], v[152:155], v[160:163], v[122:125]
	v_mfma_f32_16x16x32_bf16 v[118:121], v[140:143], v[168:171], v[118:121]
	v_mfma_f32_16x16x32_bf16 v[114:117], v[152:155], v[168:171], v[114:117]
	v_mfma_f32_16x16x32_bf16 v[94:97], v[140:143], v[176:179], v[94:97]
	v_mfma_f32_16x16x32_bf16 v[90:93], v[152:155], v[176:179], v[90:93]
	v_mfma_f32_16x16x32_bf16 v[86:89], v[140:143], v[184:187], v[86:89]
	v_mfma_f32_16x16x32_bf16 v[82:85], v[152:155], v[184:187], v[82:85]
	s_setprio 0
	s_barrier
	s_add_i32 s46, 0, 0x1c000
	s_add_i32 s0, s11, s50
	v_add_u32_e32 v210, s46, v145
	v_lshl_add_u64 v[214:215], v[214:215], 0, s[16:17]
	s_mov_b32 m0, s0
	ds_read_b128 v[188:191], v210
	ds_read_b128 v[192:195], v210 offset:1024
	ds_read_b128 v[196:199], v210 offset:2048
	ds_read_b128 v[210:213], v210 offset:3072
	global_load_lds_dwordx4 v[214:215], off
	v_lshl_add_u64 v[214:215], v[216:217], 0, s[16:17]
	s_add_i32 m0, s0, 0x2000
	s_nop 0
	global_load_lds_dwordx4 v[214:215], off
	s_barrier
	s_waitcnt lgkmcnt(0)
	s_setprio 1
	s_waitcnt lgkmcnt(0)
	v_mfma_f32_16x16x32_bf16 v[110:113], v[188:191], v[156:159], v[110:113]
	v_mfma_f32_16x16x32_bf16 v[106:109], v[196:199], v[156:159], v[106:109]
	v_mfma_f32_16x16x32_bf16 v[102:105], v[188:191], v[164:167], v[102:105]
	v_mfma_f32_16x16x32_bf16 v[98:101], v[196:199], v[164:167], v[98:101]
	v_mfma_f32_16x16x32_bf16 v[78:81], v[188:191], v[172:175], v[78:81]
	v_mfma_f32_16x16x32_bf16 v[74:77], v[196:199], v[172:175], v[74:77]
	v_mfma_f32_16x16x32_bf16 v[70:73], v[188:191], v[180:183], v[70:73]
	v_mfma_f32_16x16x32_bf16 v[66:69], v[196:199], v[180:183], v[66:69]
	v_mfma_f32_16x16x32_bf16 v[110:113], v[192:195], v[160:163], v[110:113]
	v_mfma_f32_16x16x32_bf16 v[106:109], v[210:213], v[160:163], v[106:109]
	v_mfma_f32_16x16x32_bf16 v[102:105], v[192:195], v[168:171], v[102:105]
	v_mfma_f32_16x16x32_bf16 v[98:101], v[210:213], v[168:171], v[98:101]
	v_mfma_f32_16x16x32_bf16 v[78:81], v[192:195], v[176:179], v[78:81]
	v_mfma_f32_16x16x32_bf16 v[74:77], v[210:213], v[176:179], v[74:77]
	v_mfma_f32_16x16x32_bf16 v[70:73], v[192:195], v[184:187], v[70:73]
	v_mfma_f32_16x16x32_bf16 v[66:69], v[210:213], v[184:187], v[66:69]
	s_setprio 0
	s_mov_b32 m0, s55
	v_lshl_add_u64 v[214:215], v[218:219], 0, s[16:17]
	s_barrier
	ds_read_b128 v[156:159], v147 offset:49152
	ds_read_b128 v[160:163], v147 offset:50176
	ds_read_b128 v[164:167], v147 offset:51200
	ds_read_b128 v[168:171], v147 offset:52224
	ds_read_b128 v[172:175], v147 offset:53248
	ds_read_b128 v[176:179], v147 offset:54272
	ds_read_b128 v[180:183], v147 offset:55296
	ds_read_b128 v[184:187], v147 offset:56320
	global_load_lds_dwordx4 v[214:215], off
	v_lshl_add_u64 v[214:215], v[220:221], 0, s[16:17]
	s_mov_b32 m0, s56
	s_nop 0
	global_load_lds_dwordx4 v[214:215], off
	s_waitcnt vmcnt(10)
	s_barrier
; #define PG8_STAGE(bufoff, gbase, voff) do { _Pragma("unroll") for (int _i = 0; _i < 2; ++_i) \
;         __builtin_amdgcn_global_load_lds((const unsigned*)((const char*)(gbase) + (voff)[_i]), (LAS unsigned*)(lds + (bufoff) + ldsw + _i * 8192), 16, 0, 0); } while (0)
; #define PG8_LDA(dst, b, h) do { _Pragma("unroll") for (int m = 0; m < 4; ++m) _Pragma("unroll") for (int k = 0; k < 2; ++k) dst[m][k] = *(const LAS bf16x8*)(lds + PG8_SA(b, h) + aoff + m * 2048 + k * 1024); } while (0)
; #define PG8_WAIT_V(n) asm volatile("s_waitcnt vmcnt(" #n ")" ::: "memory")
; #define PG8_WAIT_L(n) asm volatile("s_waitcnt lgkmcnt(" #n ")" ::: "memory")
; #define PG8_BAR __builtin_amdgcn_s_barrier()
; #define PG8_SCHED __builtin_amdgcn_sched_barrier(0)
; #define PG8_WAIT_V(n) asm volatile("s_waitcnt vmcnt(" #n ")" ::: "memory")
; template <class Epi, class Sched>
; DI void gemm_phase(LAS unsigned char* lds, const Gemm g, const Sched& S, const Epi& E) {
;     ...
;             PG8_BAR; PG8_WAIT_L(0); PG8_MMA(0, 1, At, B1); PG8_BAR;
;             PG8_LDA(At, 1, 1); PG8_STAGE(PG8_SA(1, 0), a3, voffA);
;             PG8_BAR; PG8_WAIT_L(0); PG8_MMA(1, 0, At, B0); PG8_BAR; PG8_SCHED;
;             PG8_STAGE(PG8_SB(1, 1), b3 + hstepB, voffB);
;             PG8_WAIT_V(6); PG8_BAR; PG8_MMA(1, 1, At, B1); PG8_BAR;
;         }
;         if constexpr (!Epi::AFTER_DRAIN) { E(acc, cur, wr, wc, fr, fq); S.done(cur); }
;   DI void operator()(const f32x4 (&acc)[2][2][4][2], const Unit& u, int wr, int wc, int fr, int fq) const {
;     const int row0 = u.pm * BM + wr * 64 + fr, col0 = u.pn * BM + wc * 32 + 4 * fq;
; #pragma unroll
;     for (int ai = 0; ai < 2; ++ai)
; #pragma unroll
;       for (int mp = 0; mp < 2; ++mp) {
;         f32x4 xv[2][2][2];
; #pragma unroll
;         for (int mm = 0; mm < 2; ++mm)
; #pragma unroll
;           for (int bj = 0; bj < 2; ++bj)
; #pragma unroll
;             for (int n = 0; n < 2; ++n)
;               xv[mm][bj][n] = *(const f32x4*)(X + (size_t)(row0 + ai * HALF + (mp * 2 + mm) * 16) * 1024 + col0 + bj * HALF + n * 16);
; #pragma unroll
;         for (int mm = 0; mm < 2; ++mm)
; #pragma unroll
;           for (int bj = 0; bj < 2; ++bj)
; #pragma unroll
;             for (int n = 0; n < 2; ++n)
;               *(f32x4*)(O + (size_t)(row0 + ai * HALF + (mp * 2 + mm) * 16) * 1024 + col0 + bj * HALF + n * 16) = xv[mm][bj][n] + acc[ai][bj][mp * 2 + mm][n];
;       }
	s_waitcnt lgkmcnt(0)
	s_setprio 1
	s_waitcnt lgkmcnt(0)
	v_mfma_f32_16x16x32_bf16 v[62:65], v[136:139], v[156:159], v[62:65]
	v_mfma_f32_16x16x32_bf16 v[58:61], v[148:151], v[156:159], v[58:61]
	v_mfma_f32_16x16x32_bf16 v[54:57], v[136:139], v[164:167], v[54:57]
	v_mfma_f32_16x16x32_bf16 v[50:53], v[148:151], v[164:167], v[50:53]
	v_mfma_f32_16x16x32_bf16 v[30:33], v[136:139], v[172:175], v[30:33]
	v_mfma_f32_16x16x32_bf16 v[26:29], v[148:151], v[172:175], v[26:29]
	v_mfma_f32_16x16x32_bf16 v[22:25], v[136:139], v[180:183], v[22:25]
	v_mfma_f32_16x16x32_bf16 v[18:21], v[148:151], v[180:183], v[18:21]
	v_mfma_f32_16x16x32_bf16 v[62:65], v[140:143], v[160:163], v[62:65]
	v_mfma_f32_16x16x32_bf16 v[58:61], v[152:155], v[160:163], v[58:61]
	v_mfma_f32_16x16x32_bf16 v[54:57], v[140:143], v[168:171], v[54:57]
	v_mfma_f32_16x16x32_bf16 v[50:53], v[152:155], v[168:171], v[50:53]
	v_mfma_f32_16x16x32_bf16 v[30:33], v[140:143], v[176:179], v[30:33]
	v_mfma_f32_16x16x32_bf16 v[26:29], v[152:155], v[176:179], v[26:29]
	v_mfma_f32_16x16x32_bf16 v[22:25], v[140:143], v[184:187], v[22:25]
	v_mfma_f32_16x16x32_bf16 v[18:21], v[152:155], v[184:187], v[18:21]
	s_setprio 0
	s_barrier
	s_add_u32 s0, s44, 0x40080
	s_addc_u32 s1, s45, 0
	s_add_i32 s11, s46, s50
	v_lshl_add_u64 v[136:137], s[0:1], 0, v[0:1]
	s_mov_b32 m0, s11
	s_nop 0
	global_load_lds_dwordx4 v[136:137], off
	v_lshl_add_u64 v[136:137], s[0:1], 0, v[130:131]
	s_add_i32 m0, s11, 0x2000
	s_nop 0
	global_load_lds_dwordx4 v[136:137], off
	v_add_u32_e32 v152, 0x10000, v145
	ds_read_b128 v[136:139], v152
	ds_read_b128 v[140:143], v152 offset:1024
	ds_read_b128 v[148:151], v152 offset:2048
	ds_read_b128 v[152:155], v152 offset:3072
	s_waitcnt vmcnt(6)
	s_barrier
	s_setprio 1
	v_mfma_f32_16x16x32_bf16 v[46:49], v[188:191], v[156:159], v[46:49]
	v_mfma_f32_16x16x32_bf16 v[42:45], v[196:199], v[156:159], v[42:45]
	v_mfma_f32_16x16x32_bf16 v[38:41], v[188:191], v[164:167], v[38:41]
	v_mfma_f32_16x16x32_bf16 v[34:37], v[196:199], v[164:167], v[34:37]
	v_mfma_f32_16x16x32_bf16 v[14:17], v[188:191], v[172:175], v[14:17]
	v_mfma_f32_16x16x32_bf16 v[10:13], v[196:199], v[172:175], v[10:13]
	v_mfma_f32_16x16x32_bf16 v[6:9], v[188:191], v[180:183], v[6:9]
	v_mfma_f32_16x16x32_bf16 v[2:5], v[196:199], v[180:183], v[2:5]
	v_mfma_f32_16x16x32_bf16 v[46:49], v[192:195], v[160:163], v[46:49]
	v_mfma_f32_16x16x32_bf16 v[42:45], v[210:213], v[160:163], v[42:45]
	v_mfma_f32_16x16x32_bf16 v[38:41], v[192:195], v[168:171], v[38:41]
	v_mfma_f32_16x16x32_bf16 v[34:37], v[210:213], v[168:171], v[34:37]
	v_mfma_f32_16x16x32_bf16 v[14:17], v[192:195], v[176:179], v[14:17]
	v_mfma_f32_16x16x32_bf16 v[10:13], v[210:213], v[176:179], v[10:13]
	v_mfma_f32_16x16x32_bf16 v[6:9], v[192:195], v[184:187], v[6:9]
	v_mfma_f32_16x16x32_bf16 v[2:5], v[210:213], v[184:187], v[2:5]
	s_setprio 0
	s_add_i32 s60, s60, 2
	s_add_u32 s58, s58, 0x100
	s_addc_u32 s59, s59, 0
	s_add_u32 s42, s42, 0x100
	s_addc_u32 s43, s43, 0
	s_cmp_gt_u32 s60, 13
	s_barrier
	s_cbranch_scc0 .LBB0_1039
	s_waitcnt lgkmcnt(0)
	v_lshl_or_b32 v136, s41, 8, v146
	v_lshl_add_u32 v142, s40, 8, v144
	v_ashrrev_i32_e32 v137, 31, v136
	v_lshlrev_b64 v[136:137], 2, v[136:137]
	v_ashrrev_i32_e32 v143, 31, v142
	v_or_b32_e32 v164, 16, v142
	v_lshl_add_u64 v[138:139], s[2:3], 0, v[136:137]
	v_lshlrev_b64 v[140:141], 12, v[142:143]
	v_ashrrev_i32_e32 v165, 31, v164
	v_lshl_add_u64 v[160:161], v[138:139], 0, v[140:141]
	v_lshlrev_b64 v[180:181], 12, v[164:165]
	global_load_dwordx4 v[148:151], v[160:161], off
	global_load_dwordx4 v[152:155], v[160:161], off offset:64
	global_load_dwordx4 v[156:159], v[160:161], off offset:512
	s_nop 0
	global_load_dwordx4 v[160:163], v[160:161], off offset:576
	v_lshl_add_u64 v[176:177], v[138:139], 0, v[180:181]
	global_load_dwordx4 v[164:167], v[176:177], off
	global_load_dwordx4 v[168:171], v[176:177], off offset:64
	global_load_dwordx4 v[172:175], v[176:177], off offset:512
	s_nop 0
	global_load_dwordx4 v[176:179], v[176:177], off offset:576
	s_mov_b64 s[40:41], 0x80000
	s_mov_b64 s[0:1], 0x90000
	s_and_b64 vcc, exec, s[36:37]
	s_mov_b64 s[42:43], s[38:39]
	s_mov_b64 s[44:45], s[34:35]
	s_waitcnt vmcnt(0)
	v_pk_add_f32 v[126:127], v[126:127], v[148:149]
	v_lshl_add_u64 v[148:149], s[4:5], 0, v[140:141]
	v_lshl_add_u64 v[148:149], v[148:149], 0, v[136:137]
	v_pk_add_f32 v[112:113], v[112:113], v[158:159]
	v_pk_add_f32 v[110:111], v[110:111], v[156:157]
	global_store_dwordx4 v[148:149], v[110:113], off offset:512 sc1
	v_pk_add_f32 v[100:101], v[100:101], v[178:179]
	v_pk_add_f32 v[98:99], v[98:99], v[176:177]
	v_lshl_add_u64 v[110:111], s[4:5], 0, v[180:181]
	v_lshl_add_u64 v[110:111], v[110:111], 0, v[136:137]
	v_pk_add_f32 v[108:109], v[108:109], v[162:163]
	v_pk_add_f32 v[106:107], v[106:107], v[160:161]
	global_store_dwordx4 v[110:111], v[98:101], off offset:576 sc1
	v_pk_add_f32 v[128:129], v[128:129], v[150:151]
	v_pk_add_f32 v[124:125], v[124:125], v[154:155]
	v_or_b32_e32 v98, 32, v142
	v_pk_add_f32 v[122:123], v[122:123], v[152:153]
	global_store_dwordx4 v[148:149], v[106:109], off offset:576 sc1
	v_ashrrev_i32_e32 v99, 31, v98
	global_store_dwordx4 v[148:149], v[126:129], off sc1
	v_pk_add_f32 v[108:109], v[120:121], v[166:167]
	v_pk_add_f32 v[106:107], v[118:119], v[164:165]
	global_store_dwordx4 v[148:149], v[122:125], off offset:64 sc1
	global_store_dwordx4 v[110:111], v[106:109], off sc1
	v_pk_add_f32 v[104:105], v[104:105], v[174:175]
	v_pk_add_f32 v[102:103], v[102:103], v[172:173]
	v_pk_add_f32 v[108:109], v[116:117], v[170:171]
	v_pk_add_f32 v[106:107], v[114:115], v[168:169]
	v_lshlrev_b64 v[148:149], 12, v[98:99]
	v_or_b32_e32 v114, 48, v142
	global_store_dwordx4 v[110:111], v[106:109], off offset:64 sc1
	global_store_dwordx4 v[110:111], v[102:105], off offset:512 sc1
	v_lshl_add_u64 v[110:111], v[138:139], 0, v[148:149]
	v_ashrrev_i32_e32 v115, 31, v114
	global_load_dwordx4 v[98:101], v[110:111], off
	global_load_dwordx4 v[102:105], v[110:111], off offset:64
	global_load_dwordx4 v[106:109], v[110:111], off offset:512
	s_nop 0
	global_load_dwordx4 v[110:113], v[110:111], off offset:576
	v_lshlrev_b64 v[142:143], 12, v[114:115]
	v_lshl_add_u64 v[126:127], v[138:139], 0, v[142:143]
	global_load_dwordx4 v[114:117], v[126:127], off
	global_load_dwordx4 v[118:121], v[126:127], off offset:64
	global_load_dwordx4 v[122:125], v[126:127], off offset:512
	s_nop 0
	global_load_dwordx4 v[126:129], v[126:127], off offset:576
	s_waitcnt vmcnt(0)
;   DI void operator()(const f32x4 (&acc)[2][2][4][2], const Unit& u, int wr, int wc, int fr, int fq) const {
;     const int row0 = u.pm * BM + wr * 64 + fr, col0 = u.pn * BM + wc * 32 + 4 * fq;
; #pragma unroll
;     for (int ai = 0; ai < 2; ++ai)
; #pragma unroll
;       for (int mp = 0; mp < 2; ++mp) {
;         f32x4 xv[2][2][2];
; #pragma unroll
;         for (int mm = 0; mm < 2; ++mm)
; #pragma unroll
;           for (int bj = 0; bj < 2; ++bj)
; #pragma unroll
;             for (int n = 0; n < 2; ++n)
;               xv[mm][bj][n] = *(const f32x4*)(X + (size_t)(row0 + ai * HALF + (mp * 2 + mm) * 16) * 1024 + col0 + bj * HALF + n * 16);
; #pragma unroll
;         for (int mm = 0; mm < 2; ++mm)
; #pragma unroll
;           for (int bj = 0; bj < 2; ++bj)
; #pragma unroll
;             for (int n = 0; n < 2; ++n)
;               *(f32x4*)(O + (size_t)(row0 + ai * HALF + (mp * 2 + mm) * 16) * 1024 + col0 + bj * HALF + n * 16) = xv[mm][bj][n] + acc[ai][bj][mp * 2 + mm][n];
;       }
	v_pk_add_f32 v[94:95], v[94:95], v[98:99]
	v_lshl_add_u64 v[98:99], s[4:5], 0, v[148:149]
	v_lshl_add_u64 v[98:99], v[98:99], 0, v[136:137]
	v_pk_add_f32 v[80:81], v[80:81], v[108:109]
	v_pk_add_f32 v[78:79], v[78:79], v[106:107]
	global_store_dwordx4 v[98:99], v[78:81], off offset:512 sc1
	v_pk_add_f32 v[76:77], v[76:77], v[112:113]
	v_pk_add_f32 v[74:75], v[74:75], v[110:111]
	v_lshl_add_u64 v[78:79], s[4:5], 0, v[142:143]
	v_pk_add_f32 v[96:97], v[96:97], v[100:101]
	v_pk_add_f32 v[92:93], v[92:93], v[104:105]
	v_pk_add_f32 v[90:91], v[90:91], v[102:103]
	global_store_dwordx4 v[98:99], v[74:77], off offset:576 sc1
	v_lshl_add_u64 v[78:79], v[78:79], 0, v[136:137]
	global_store_dwordx4 v[98:99], v[94:97], off sc1
	v_pk_add_f32 v[76:77], v[88:89], v[116:117]
	v_pk_add_f32 v[74:75], v[86:87], v[114:115]
	global_store_dwordx4 v[98:99], v[90:93], off offset:64 sc1
	global_store_dwordx4 v[78:79], v[74:77], off sc1
	v_pk_add_f32 v[72:73], v[72:73], v[124:125]
	v_pk_add_f32 v[70:71], v[70:71], v[122:123]
	v_pk_add_f32 v[76:77], v[84:85], v[120:121]
	v_pk_add_f32 v[74:75], v[82:83], v[118:119]
	v_pk_add_f32 v[68:69], v[68:69], v[128:129]
	v_pk_add_f32 v[66:67], v[66:67], v[126:127]
	v_lshl_add_u64 v[98:99], v[140:141], 0, s[40:41]
	global_store_dwordx4 v[78:79], v[74:77], off offset:64 sc1
	global_store_dwordx4 v[78:79], v[70:73], off offset:512 sc1
	global_store_dwordx4 v[78:79], v[66:69], off offset:576 sc1
	v_lshl_add_u64 v[78:79], v[138:139], 0, v[98:99]
	global_load_dwordx4 v[66:69], v[78:79], off
	global_load_dwordx4 v[70:73], v[78:79], off offset:64
	global_load_dwordx4 v[74:77], v[78:79], off offset:512
	s_nop 0
	global_load_dwordx4 v[78:81], v[78:79], off offset:576
	v_lshl_add_u64 v[100:101], v[140:141], 0, s[0:1]
	v_lshl_add_u64 v[94:95], v[138:139], 0, v[100:101]
	global_load_dwordx4 v[82:85], v[94:95], off
	global_load_dwordx4 v[86:89], v[94:95], off offset:64
	global_load_dwordx4 v[90:93], v[94:95], off offset:512
	s_nop 0
	global_load_dwordx4 v[94:97], v[94:95], off offset:576
	s_mov_b64 s[40:41], 0xa0000
	s_mov_b64 s[0:1], 0xb0000
	s_waitcnt vmcnt(0)
	v_pk_add_f32 v[62:63], v[62:63], v[66:67]
	v_lshl_add_u64 v[66:67], s[4:5], 0, v[98:99]
	v_lshl_add_u64 v[66:67], v[66:67], 0, v[136:137]
	v_pk_add_f32 v[48:49], v[48:49], v[76:77]
	v_pk_add_f32 v[46:47], v[46:47], v[74:75]
	global_store_dwordx4 v[66:67], v[46:49], off offset:512 sc1
	v_pk_add_f32 v[44:45], v[44:45], v[80:81]
	v_pk_add_f32 v[42:43], v[42:43], v[78:79]
	v_lshl_add_u64 v[46:47], s[4:5], 0, v[100:101]
	v_pk_add_f32 v[64:65], v[64:65], v[68:69]
	v_pk_add_f32 v[60:61], v[60:61], v[72:73]
	v_pk_add_f32 v[58:59], v[58:59], v[70:71]
	global_store_dwordx4 v[66:67], v[42:45], off offset:576 sc1
	v_lshl_add_u64 v[46:47], v[46:47], 0, v[136:137]
	global_store_dwordx4 v[66:67], v[62:65], off sc1
	v_pk_add_f32 v[44:45], v[56:57], v[84:85]
	v_pk_add_f32 v[42:43], v[54:55], v[82:83]
	global_store_dwordx4 v[66:67], v[58:61], off offset:64 sc1
	global_store_dwordx4 v[46:47], v[42:45], off sc1
	v_pk_add_f32 v[40:41], v[40:41], v[92:93]
	v_pk_add_f32 v[38:39], v[38:39], v[90:91]
	v_pk_add_f32 v[44:45], v[52:53], v[88:89]
	v_pk_add_f32 v[42:43], v[50:51], v[86:87]
	v_pk_add_f32 v[36:37], v[36:37], v[96:97]
	v_pk_add_f32 v[34:35], v[34:35], v[94:95]
	v_lshl_add_u64 v[66:67], v[140:141], 0, s[40:41]
	global_store_dwordx4 v[46:47], v[42:45], off offset:64 sc1
	global_store_dwordx4 v[46:47], v[38:41], off offset:512 sc1
	global_store_dwordx4 v[46:47], v[34:37], off offset:576 sc1
	v_lshl_add_u64 v[46:47], v[138:139], 0, v[66:67]
	global_load_dwordx4 v[34:37], v[46:47], off
	global_load_dwordx4 v[38:41], v[46:47], off offset:64
	global_load_dwordx4 v[42:45], v[46:47], off offset:512
	s_nop 0
	global_load_dwordx4 v[46:49], v[46:47], off offset:576
	v_lshl_add_u64 v[68:69], v[140:141], 0, s[0:1]
	v_lshl_add_u64 v[62:63], v[138:139], 0, v[68:69]
	global_load_dwordx4 v[50:53], v[62:63], off
	global_load_dwordx4 v[54:57], v[62:63], off offset:64
	global_load_dwordx4 v[58:61], v[62:63], off offset:512
	s_nop 0
	global_load_dwordx4 v[62:65], v[62:63], off offset:576
	s_mov_b32 s41, s8
	s_mov_b32 s40, s12
	s_waitcnt vmcnt(0)
	v_pk_add_f32 v[30:31], v[30:31], v[34:35]
	v_lshl_add_u64 v[34:35], s[4:5], 0, v[66:67]
	v_lshl_add_u64 v[34:35], v[34:35], 0, v[136:137]
	v_pk_add_f32 v[16:17], v[16:17], v[44:45]
	v_pk_add_f32 v[14:15], v[14:15], v[42:43]
	global_store_dwordx4 v[34:35], v[14:17], off offset:512 sc1
	v_pk_add_f32 v[12:13], v[12:13], v[48:49]
	v_pk_add_f32 v[10:11], v[10:11], v[46:47]
	v_lshl_add_u64 v[14:15], s[4:5], 0, v[68:69]
	global_store_dwordx4 v[34:35], v[10:13], off offset:576 sc1
	v_lshl_add_u64 v[14:15], v[14:15], 0, v[136:137]
	v_pk_add_f32 v[32:33], v[32:33], v[36:37]
	v_pk_add_f32 v[12:13], v[24:25], v[52:53]
	v_pk_add_f32 v[10:11], v[22:23], v[50:51]
	v_pk_add_f32 v[28:29], v[28:29], v[40:41]
	v_pk_add_f32 v[26:27], v[26:27], v[38:39]
	global_store_dwordx4 v[14:15], v[10:13], off sc1
	v_pk_add_f32 v[8:9], v[8:9], v[60:61]
	v_pk_add_f32 v[6:7], v[6:7], v[58:59]
	v_pk_add_f32 v[12:13], v[20:21], v[56:57]
	v_pk_add_f32 v[10:11], v[18:19], v[54:55]
	v_pk_add_f32 v[4:5], v[4:5], v[64:65]
	v_pk_add_f32 v[2:3], v[2:3], v[62:63]
	global_store_dwordx4 v[34:35], v[30:33], off sc1
	global_store_dwordx4 v[34:35], v[26:29], off offset:64 sc1
	global_store_dwordx4 v[14:15], v[10:13], off offset:64 sc1
	global_store_dwordx4 v[14:15], v[6:9], off offset:512 sc1
	global_store_dwordx4 v[14:15], v[2:5], off offset:576 sc1
	s_cbranch_vccz .LBB0_1032
	s_waitcnt vmcnt(0)
	s_cmpk_gt_u32 s20, 0xff
	s_cbranch_scc1 .LBB0_1043
	s_barrier
